# pool-branch weight fold: inner loop fully unrolled with 3 rotating register sets and loads issued two iterations ahead; fold spread over all workgroups (one tile each) instead of the weight-prep half
# speedup vs baseline: 1.0109x; 1.0109x over previous
; DI int get_bid() { int b = blockIdx.x; asm volatile("" : "+s"(b)); return b; }
; DI int get_grid() { int g = gridDim.x; asm volatile("" : "+s"(g)); return g; }
;   const int GRD0 = get_grid(); const int GRD = GRD0 / gdiv; const int BID = (get_bid() + bid_shift) % GRD0;
;   if (BID >= GRD) return;
;     ...
;   for (int j = 0; j < NJ; ++j) {
;     if (!((mask >> j) & 1)) continue;
;     int nk = Kd[j] / 64, nn = Nd[j] / 256, cnt = nk * nn;
;     int first = (BID - base % GRD + GRD) % GRD;
;     for (int i = first; i < cnt; i += GRD) transpose_tile(WV, sm, src[j], lds_[j], dst[j], Kd[j], (i / nn) * 64, (i % nn) * 256);
.LBB0_373:
	v_readlane_b32 s1, v255, 21
	s_lshr_b32 s0, s1, 31
	s_add_i32 s0, s1, s0
	s_mov_b32 s1, s53
	s_abs_i32 s4, s1
	v_cvt_f32_u32_e32 v0, s4
	s_lshr_b32 s5, s1, 31
	s_add_i32 s1, s1, s5
	s_ashr_i32 s20, s1, 1
	v_rcp_iflag_f32_e32 v0, v0
	s_mov_b32 s1, s57
	s_sub_i32 s5, 0, s4
	s_ashr_i32 s0, s0, 1
	v_mul_f32_e32 v0, 0x4f7ffffe, v0
	v_cvt_u32_f32_e32 v0, v0
	s_add_i32 s1, s1, s0
	s_ashr_i32 s0, s1, 31
	v_readfirstlane_b32 s8, v0
	s_mul_i32 s5, s5, s8
	s_mul_hi_u32 s5, s8, s5
	s_abs_i32 s1, s1
	s_add_i32 s8, s8, s5
	s_mul_hi_u32 s5, s1, s8
	s_mul_i32 s5, s5, s4
	s_sub_i32 s1, s1, s5
	s_sub_i32 s5, s1, s4
	s_cmp_ge_u32 s1, s4
	s_cselect_b32 s1, s5, s1
	s_sub_i32 s5, s1, s4
	s_cmp_ge_u32 s1, s4
	s_cselect_b32 s1, s5, s1
	s_xor_b32 s1, s1, s0
	s_sub_i32 s21, s1, s0
	v_readlane_b32 s4, v255, 22
	v_readlane_b32 s5, v255, 23
	s_load_dwordx8 s[8:15], s[4:5], 0x70
	s_ashr_i32 s47, s46, 31
	s_lshl_b64 s[0:1], s[46:47], 24
	s_load_dwordx4 s[16:19], s[4:5], 0x98
	s_movk_i32 s28, 0x404
	s_waitcnt lgkmcnt(0)
	s_add_u32 s23, s12, s0
	s_addc_u32 s24, s13, s1
	s_abs_i32 s12, s20
	v_cvt_f32_u32_e32 v0, s12
	s_sub_i32 s4, 0, s12
	s_add_i32 s13, s21, s20
	s_abs_i32 s1, s13
	v_rcp_iflag_f32_e32 v0, v0
	s_ashr_i32 s0, s13, 31
	v_readlane_b32 s29, v255, 33
	v_readlane_b32 s30, v255, 34
	v_mul_f32_e32 v0, 0x4f7ffffe, v0
	v_cvt_u32_f32_e32 v0, v0
	s_nop 0
	v_readfirstlane_b32 s22, v0
	s_mul_i32 s4, s4, s22
	s_mul_hi_u32 s4, s22, s4
	s_add_i32 s22, s22, s4
	s_mul_hi_u32 s4, s1, s22
	s_mul_i32 s4, s4, s12
	s_sub_i32 s1, s1, s4
	s_sub_i32 s4, s1, s12
	s_cmp_ge_u32 s1, s12
	s_cselect_b32 s1, s4, s1
	s_sub_i32 s4, s1, s12
	s_cmp_ge_u32 s1, s12
	s_cselect_b32 s1, s4, s1
	s_xor_b32 s1, s1, s0
	s_sub_i32 s0, s1, s0
	s_cmp_ge_i32 s21, s20
	s_cbranch_scc1 .Lwp_poolall
	s_cmp_gt_i32 s0, 63
	s_cbranch_scc1 .LBB0_377
	s_lshl_b32 s1, s0, 8
	s_lshl_b32 s25, s20, 8
	s_ashr_i32 s4, s0, 31
	s_lshr_b32 s4, s4, 30
	s_add_i32 s4, s0, s4
	s_ashr_i32 s5, s4, 2
	s_lshl_b32 s4, s5, 6
	s_lshl_b32 s5, s5, 10
	v_mbcnt_lo_u32_b32 v0, -1, 0
	v_mbcnt_hi_u32_b32 v0, -1, v0
	s_sub_i32 s26, s1, s5
	v_add_u32_e32 v2, s3, v0
	v_lshlrev_b32_e32 v3, 4, v0
	v_lshlrev_b32_e32 v4, 3, v0
	v_ashrrev_i32_e32 v5, 6, v2
	v_and_b32_e32 v0, 0x3f0, v3
	v_and_b32_e32 v42, 56, v4
	v_ashrrev_i32_e32 v3, 3, v2
	v_add_u32_e32 v4, 0x200, v2
	v_add_u32_e32 v6, 0x400, v2
	v_add_u32_e32 v2, 0x600, v2
	s_ashr_i32 s27, s26, 31
	v_mul_lo_u32 v7, v5, s28
	v_mad_u32_u24 v8, v42, s28, 0
	v_ashrrev_i32_e32 v4, 3, v4
	v_ashrrev_i32_e32 v9, 3, v2
	v_add_u32_e32 v2, s4, v5
	v_subrev_u32_e32 v5, s5, v3
	s_lshl_b64 s[26:27], s[26:27], 2
	v_ashrrev_i32_e32 v6, 3, v6
	v_add3_u32 v44, 0, v0, v7
	v_lshl_add_u32 v46, v4, 2, v8
	v_subrev_u32_e32 v7, s5, v4
	v_add_u32_e32 v4, s1, v5
	s_add_u32 s26, s23, s26
	v_lshl_add_u32 v45, v3, 2, v8
	v_lshl_add_u32 v47, v6, 2, v8
	v_lshl_add_u32 v48, v9, 2, v8
	v_subrev_u32_e32 v8, s5, v6
	v_ashrrev_i32_e32 v3, 31, v2
	v_add_u32_e32 v6, s1, v7
	v_ashrrev_i32_e32 v5, 31, v4
	s_addc_u32 s27, s24, s27
	v_subrev_u32_e32 v9, s5, v9
	v_add_u32_e32 v8, s1, v8
	v_lshlrev_b64 v[2:3], 12, v[2:3]
	v_ashrrev_i32_e32 v7, 31, v6
	v_lshlrev_b64 v[34:35], 11, v[4:5]
	v_lshl_add_u64 v[4:5], s[26:27], 0, v[0:1]
	v_add_u32_e32 v10, s1, v9
	v_ashrrev_i32_e32 v9, 31, v8
	v_lshlrev_b64 v[36:37], 11, v[6:7]
	v_lshl_add_u64 v[6:7], v[4:5], 0, v[2:3]
	v_lshlrev_b64 v[38:39], 11, v[8:9]
	v_add_co_u32_e32 v8, vcc, s38, v6
	v_ashrrev_i32_e32 v11, 31, v10
	s_nop 0
	v_addc_co_u32_e32 v9, vcc, 0, v7, vcc
	v_lshlrev_b64 v[40:41], 11, v[10:11]
	v_add_co_u32_e32 v10, vcc, s36, v6
	global_load_dwordx4 v[2:5], v[6:7], off
	s_nop 0
	v_addc_co_u32_e32 v11, vcc, 0, v7, vcc
	v_add_co_u32_e32 v14, vcc, s37, v6
	s_ashr_i32 s5, s4, 31
	s_nop 0
	v_addc_co_u32_e32 v15, vcc, 0, v7, vcc
	v_add_co_u32_e32 v18, vcc, s39, v6
	s_lshl_b64 s[4:5], s[4:5], 1
	s_nop 0
	v_addc_co_u32_e32 v19, vcc, 0, v7, vcc
	v_add_co_u32_e32 v22, vcc, s40, v6
	s_add_u32 s4, s29, s4
	s_nop 0
	v_addc_co_u32_e32 v23, vcc, 0, v7, vcc
	v_add_co_u32_e32 v26, vcc, s41, v6
	v_lshlrev_b32_e32 v0, 1, v42
	s_nop 0
	v_addc_co_u32_e32 v27, vcc, 0, v7, vcc
	v_add_co_u32_e32 v30, vcc, s42, v6
	s_addc_u32 s5, s30, s5
	s_nop 0
	v_addc_co_u32_e32 v31, vcc, 0, v7, vcc
	global_load_dwordx4 v[6:9], v[8:9], off
	s_nop 0
	global_load_dwordx4 v[10:13], v[10:11], off
	s_nop 0
	global_load_dwordx4 v[14:17], v[14:15], off
	s_nop 0
	global_load_dwordx4 v[18:21], v[18:19], off
	s_nop 0
	global_load_dwordx4 v[22:25], v[22:23], off
	s_nop 0
	global_load_dwordx4 v[26:29], v[26:27], off
	s_nop 0
	global_load_dwordx4 v[30:33], v[30:31], off
	v_add_u32_e32 v49, 0x2020, v44
	v_add_u32_e32 v50, 0x2028, v44
	v_add_u32_e32 v51, 0x4040, v44
	v_add_u32_e32 v52, 0x4048, v44
	v_add_u32_e32 v53, 0x6060, v44
	v_add_u32_e32 v54, 0x6068, v44
	v_add_u32_e32 v55, 0x8080, v44
	v_add_u32_e32 v56, 0x8088, v44
	v_add_u32_e32 v57, 0xa0a0, v44
	v_add_u32_e32 v58, 0xa0a8, v44
	v_add_u32_e32 v59, 0xc0c0, v44
	v_add_u32_e32 v60, 0xc0c8, v44
	v_add_u32_e32 v61, 0xe0e0, v44
	v_add_u32_e32 v62, 0xe0e8, v44
	s_waitcnt vmcnt(0)

; DI int get_tid(int wv) { int l; asm volatile("v_mbcnt_lo_u32_b32 %0, -1, 0\n\tv_mbcnt_hi_u32_b32 %0, -1, %0" : "=v"(l)); return wv * 64 + l; }
;     ...
;   const float* pool_w = pp->in[3] + (size_t)l * 4 * 128 * 128;
;   const float* pool_s = pp->in[4] + (size_t)l * 512;
;   for (int it = GRD - 1 - BID; it < (((mask >> 12) & 1) ? 16 * 16 : 0); it += GRD) {
;     const int k0 = (it >> 4) * 32, n0 = (it & 15) * 64;
;     const int tid = get_tid(WV);
;     const int n = n0 + (tid & 63), kb = k0 + (tid >> 6) * 4, g = kb >> 7;
;     float accv[4] = {0, 0, 0, 0};
;     const float* pw = pool_w + (size_t)(g * 128 + (kb & 127)) * 128;
; #pragma unroll 2
;     for (int d = 0; d < 128; d += 4) {
;       const f32x4 ps = *(const f32x4*)(pool_s + g * 128 + d);
.LBB0_407:
.Lwp_poolall:
	s_mov_b32 s20, s53
	s_mul_i32 s24, s46, 0x700000
	s_mul_hi_i32 s23, s46, 0x700000
	s_not_b32 s0, s21
	s_add_i32 s0, s20, s0
	s_cmpk_gt_i32 s0, 0xff
	s_cbranch_scc1 .LBB0_412
	v_readlane_b32 s4, v255, 22
	v_readlane_b32 s5, v255, 23
	s_load_dwordx4 s[12:15], s[4:5], 0x18
	s_lshl_b64 s[8:9], s[46:47], 18
	s_lshl_b64 s[26:27], s[46:47], 11
	s_add_u32 s1, s10, s24
	s_addc_u32 s5, s11, s23
	s_add_u32 s4, s1, 0x7000
	s_addc_u32 s5, s5, 0
	s_lshl_b32 s1, s0, 1
	s_lshl_b32 s16, s20, 1
	s_lshl_b32 s17, s0, 6
	s_lshl_b32 s18, s20, 6
	s_waitcnt lgkmcnt(0)
	s_add_u32 s10, s14, s26
	s_addc_u32 s11, s15, s27
	s_add_u32 s10, s10, 16
	s_addc_u32 s11, s11, 0
	s_add_u32 s12, s12, s8
	s_addc_u32 s13, s13, s9

;     ...
; #pragma unroll 2
;     for (int d = 0; d < 128; d += 4) {
;       const f32x4 ps = *(const f32x4*)(pool_s + g * 128 + d);
;       float wv[4];
;       for (int q = 0; q < 4; ++q) wv[q] = ps[q] * w_branch[(long)(g * 128 + d + q) * DM + n];
;       for (int jj = 0; jj < 4; ++jj) {
;         const f32x4 p4 = *(const f32x4*)(pw + jj * 128 + d);
;         accv[jj] += p4[0] * wv[0] + p4[1] * wv[1] + p4[2] * wv[2] + p4[3] * wv[3];
;       }
;     }
.LBB0_410:
	v_add_co_u32_e32 v54, vcc, 0xffff9000, v6
	v_lshl_add_u64 v[18:19], v[8:9], 0, s[14:15]
	s_nop 0
	v_addc_co_u32_e32 v55, vcc, -1, v7, vcc
	v_add_co_u32_e32 v58, vcc, 0xffffa000, v6
	v_lshl_add_u64 v[50:51], v[12:13], 0, s[14:15]
	s_nop 0
	v_addc_co_u32_e32 v59, vcc, -1, v7, vcc
	v_add_co_u32_e32 v62, vcc, 0xffffb000, v6
	v_add_co_u32_e64 v56, s[8:9], s21, v6
	s_nop 0
	v_addc_co_u32_e32 v63, vcc, -1, v7, vcc
	v_addc_co_u32_e64 v57, s[8:9], -1, v7, s[8:9]
	global_load_dwordx4 v[14:17], v[18:19], off
	s_nop 0
	global_load_dwordx4 v[18:21], v[18:19], off offset:-16
	s_nop 0
	global_load_dwordx4 v[22:25], v[50:51], off offset:16
	global_load_dwordx4 v[26:29], v[50:51], off
	global_load_dwordx4 v[30:33], v[50:51], off offset:528
	global_load_dwordx4 v[34:37], v[50:51], off offset:512
	global_load_dwordx4 v[38:41], v[50:51], off offset:1040
	global_load_dwordx4 v[42:45], v[50:51], off offset:1024
	global_load_dwordx4 v[46:49], v[50:51], off offset:1552
	s_nop 0
	global_load_dwordx4 v[50:53], v[50:51], off offset:1536
	s_nop 0
	global_load_dword v60, v[56:57], off offset:-4096
	global_load_dword v61, v[56:57], off
	s_nop 0
	global_load_dword v56, v[6:7], off offset:-4096
	s_nop 0
	global_load_dword v54, v[54:55], off
	s_nop 0
	global_load_dword v55, v[58:59], off
	v_add_co_u32_e32 v58, vcc, 0xffffc000, v6
	s_add_i32 s19, s19, 8
	s_nop 0
	v_addc_co_u32_e32 v59, vcc, -1, v7, vcc
	global_load_dword v62, v[62:63], off
	s_nop 0
	global_load_dword v63, v[58:59], off
	global_load_dword v57, v[6:7], off
	s_add_u32 s14, s14, 32
	s_addc_u32 s15, s15, 0
	v_lshl_add_u64 v[6:7], v[6:7], 0, s[44:45]
	v_add_co_u32_e32 v118, vcc, 0xffff9000, v6
	v_lshl_add_u64 v[82:83], v[8:9], 0, s[14:15]
	s_nop 0
	v_addc_co_u32_e32 v119, vcc, -1, v7, vcc
	v_add_co_u32_e32 v122, vcc, 0xffffa000, v6
	v_lshl_add_u64 v[114:115], v[12:13], 0, s[14:15]
	s_nop 0
	v_addc_co_u32_e32 v123, vcc, -1, v7, vcc
	v_add_co_u32_e32 v126, vcc, 0xffffb000, v6
	v_add_co_u32_e64 v120, s[8:9], s21, v6
	s_nop 0
	v_addc_co_u32_e32 v127, vcc, -1, v7, vcc
	v_addc_co_u32_e64 v121, s[8:9], -1, v7, s[8:9]
	global_load_dwordx4 v[78:81], v[82:83], off
	s_nop 0
	global_load_dwordx4 v[82:85], v[82:83], off offset:-16
	s_nop 0
	global_load_dwordx4 v[86:89], v[114:115], off offset:16
	global_load_dwordx4 v[90:93], v[114:115], off
	global_load_dwordx4 v[94:97], v[114:115], off offset:528
	global_load_dwordx4 v[98:101], v[114:115], off offset:512
	global_load_dwordx4 v[102:105], v[114:115], off offset:1040
	global_load_dwordx4 v[106:109], v[114:115], off offset:1024
	global_load_dwordx4 v[110:113], v[114:115], off offset:1552
	s_nop 0
	global_load_dwordx4 v[114:117], v[114:115], off offset:1536
	s_nop 0
	global_load_dword v124, v[120:121], off offset:-4096
	global_load_dword v125, v[120:121], off
	s_nop 0
	global_load_dword v120, v[6:7], off offset:-4096
	s_nop 0
	global_load_dword v118, v[118:119], off
	s_nop 0
	global_load_dword v119, v[122:123], off
	v_add_co_u32_e32 v122, vcc, 0xffffc000, v6
	s_add_i32 s19, s19, 8
	s_nop 0
	v_addc_co_u32_e32 v123, vcc, -1, v7, vcc
	global_load_dword v126, v[126:127], off
	s_nop 0
	global_load_dword v127, v[122:123], off
	global_load_dword v121, v[6:7], off
	s_add_u32 s14, s14, 32
	s_addc_u32 s15, s15, 0
	v_lshl_add_u64 v[6:7], v[6:7], 0, s[44:45]
	v_add_co_u32_e32 v182, vcc, 0xffff9000, v6
	v_lshl_add_u64 v[146:147], v[8:9], 0, s[14:15]
	s_nop 0
	v_addc_co_u32_e32 v183, vcc, -1, v7, vcc
	v_add_co_u32_e32 v186, vcc, 0xffffa000, v6
	v_lshl_add_u64 v[178:179], v[12:13], 0, s[14:15]
	s_nop 0
	v_addc_co_u32_e32 v187, vcc, -1, v7, vcc
	v_add_co_u32_e32 v190, vcc, 0xffffb000, v6
	v_add_co_u32_e64 v184, s[8:9], s21, v6
	s_nop 0
	v_addc_co_u32_e32 v191, vcc, -1, v7, vcc
	v_addc_co_u32_e64 v185, s[8:9], -1, v7, s[8:9]
	global_load_dwordx4 v[142:145], v[146:147], off
	s_nop 0
	global_load_dwordx4 v[146:149], v[146:147], off offset:-16
	s_nop 0
	global_load_dwordx4 v[150:153], v[178:179], off offset:16
	global_load_dwordx4 v[154:157], v[178:179], off
	global_load_dwordx4 v[158:161], v[178:179], off offset:528
	global_load_dwordx4 v[162:165], v[178:179], off offset:512
	global_load_dwordx4 v[166:169], v[178:179], off offset:1040
	global_load_dwordx4 v[170:173], v[178:179], off offset:1024
	global_load_dwordx4 v[174:177], v[178:179], off offset:1552
	s_nop 0
	global_load_dwordx4 v[178:181], v[178:179], off offset:1536
	s_nop 0
	global_load_dword v188, v[184:185], off offset:-4096
	global_load_dword v189, v[184:185], off
	s_nop 0
	global_load_dword v184, v[6:7], off offset:-4096
	s_nop 0
	global_load_dword v182, v[182:183], off
	s_nop 0
	global_load_dword v183, v[186:187], off
	v_add_co_u32_e32 v186, vcc, 0xffffc000, v6
	s_add_i32 s19, s19, 8
	s_nop 0
	v_addc_co_u32_e32 v187, vcc, -1, v7, vcc
	global_load_dword v190, v[190:191], off
	s_nop 0
	global_load_dword v191, v[186:187], off
	global_load_dword v185, v[6:7], off
	s_add_u32 s14, s14, 32
	s_addc_u32 s15, s15, 0
	v_lshl_add_u64 v[6:7], v[6:7], 0, s[44:45]
	s_waitcnt vmcnt(48)
	v_pk_mov_b32 v[58:59], v[26:27], v[34:35] op_sel:[1,0]
	v_mov_b32_e32 v27, v35
	v_mov_b32_e32 v34, v28
	v_mov_b32_e32 v35, v36
	v_mov_b32_e32 v36, v29
	v_pk_mov_b32 v[28:29], v[22:23], v[30:31] op_sel:[1,0]
	s_waitcnt vmcnt(42)
	v_pk_mul_f32 v[14:15], v[14:15], v[60:61]
	v_mov_b32_e32 v23, v31
	v_mov_b32_e32 v30, v24
	v_mul_f32_e32 v24, v15, v39
	v_pk_mul_f32 v[22:23], v[14:15], v[22:23]
	s_waitcnt vmcnt(39)
	v_pk_mul_f32 v[18:19], v[18:19], v[54:55]
	v_mov_b32_e32 v31, v32
	v_mov_b32_e32 v32, v25
	s_waitcnt vmcnt(36)
;     ...
; #pragma unroll 2
;     for (int d = 0; d < 128; d += 4) {
;       const f32x4 ps = *(const f32x4*)(pool_s + g * 128 + d);
;       float wv[4];
;       for (int q = 0; q < 4; ++q) wv[q] = ps[q] * w_branch[(long)(g * 128 + d + q) * DM + n];
;       for (int jj = 0; jj < 4; ++jj) {
;         const f32x4 p4 = *(const f32x4*)(pw + jj * 128 + d);
;         accv[jj] += p4[0] * wv[0] + p4[1] * wv[1] + p4[2] * wv[2] + p4[3] * wv[3];
;       }
;     }
	v_pk_mul_f32 v[16:17], v[16:17], v[56:57]
	v_mul_f32_e32 v56, v14, v46
	v_pk_fma_f32 v[24:25], v[14:15], v[38:39], v[24:25] op_sel_hi:[1,1,0]
	v_pk_fma_f32 v[38:39], v[14:15], v[46:47], v[56:57] op_sel_hi:[1,1,0]
	v_pk_fma_f32 v[14:15], v[14:15], v[28:29], v[22:23] op_sel:[1,0,0] op_sel_hi:[0,1,1]
	v_mul_f32_e32 v22, v19, v43
	v_mul_f32_e32 v28, v18, v50
	v_pk_mul_f32 v[26:27], v[18:19], v[26:27]
	v_pk_fma_f32 v[22:23], v[18:19], v[42:43], v[22:23] op_sel_hi:[1,1,0]
	v_pk_fma_f32 v[28:29], v[18:19], v[50:51], v[28:29] op_sel_hi:[1,1,0]
	v_pk_mul_f32 v[20:21], v[20:21], v[62:63]
	v_pk_fma_f32 v[18:19], v[18:19], v[58:59], v[26:27] op_sel:[1,0,0] op_sel_hi:[0,1,1]
	v_pk_mul_f32 v[48:49], v[16:17], v[48:49]
	v_pk_fma_f32 v[18:19], v[20:21], v[34:35], v[18:19] op_sel_hi:[0,1,1]
	v_pk_mul_f32 v[26:27], v[20:21], v[52:53]
	v_pk_fma_f32 v[14:15], v[16:17], v[30:31], v[14:15] op_sel_hi:[0,1,1]
	v_mul_f32_e32 v38, v16, v40
	v_mov_b32_e32 v25, v48
	v_mul_f32_e32 v28, v20, v44
	v_pk_fma_f32 v[18:19], v[20:21], v[36:37], v[18:19] op_sel:[1,0,0]
	v_mov_b32_e32 v23, v26
	v_mul_f32_e32 v60, v17, v41
	v_pk_fma_f32 v[14:15], v[16:17], v[32:33], v[14:15] op_sel:[1,0,0]
	v_pk_add_f32 v[16:17], v[24:25], v[38:39]
	v_mul_f32_e32 v24, v21, v45
	v_mov_b32_e32 v25, v27
	v_pk_add_f32 v[4:5], v[4:5], v[18:19]
	v_pk_add_f32 v[18:19], v[22:23], v[28:29]
	v_mov_b32_e32 v61, v49
	v_pk_add_f32 v[18:19], v[24:25], v[18:19]
	v_pk_add_f32 v[16:17], v[60:61], v[16:17]
	v_pk_add_f32 v[10:11], v[10:11], v[18:19]
	v_pk_add_f32 v[4:5], v[4:5], v[14:15]
	v_pk_add_f32 v[10:11], v[10:11], v[16:17]
	v_add_co_u32_e32 v54, vcc, 0xffff9000, v6
	v_lshl_add_u64 v[18:19], v[8:9], 0, s[14:15]
	s_nop 0
	v_addc_co_u32_e32 v55, vcc, -1, v7, vcc
	v_add_co_u32_e32 v58, vcc, 0xffffa000, v6
	v_lshl_add_u64 v[50:51], v[12:13], 0, s[14:15]
	s_nop 0
	v_addc_co_u32_e32 v59, vcc, -1, v7, vcc
	v_add_co_u32_e32 v62, vcc, 0xffffb000, v6
	v_add_co_u32_e64 v56, s[8:9], s21, v6
	s_nop 0
	v_addc_co_u32_e32 v63, vcc, -1, v7, vcc
	v_addc_co_u32_e64 v57, s[8:9], -1, v7, s[8:9]
	global_load_dwordx4 v[14:17], v[18:19], off
	s_nop 0
	global_load_dwordx4 v[18:21], v[18:19], off offset:-16
	s_nop 0
	global_load_dwordx4 v[22:25], v[50:51], off offset:16
	global_load_dwordx4 v[26:29], v[50:51], off
	global_load_dwordx4 v[30:33], v[50:51], off offset:528
	global_load_dwordx4 v[34:37], v[50:51], off offset:512
	global_load_dwordx4 v[38:41], v[50:51], off offset:1040
	global_load_dwordx4 v[42:45], v[50:51], off offset:1024
	global_load_dwordx4 v[46:49], v[50:51], off offset:1552
	s_nop 0
	global_load_dwordx4 v[50:53], v[50:51], off offset:1536
	s_nop 0
	global_load_dword v60, v[56:57], off offset:-4096
	global_load_dword v61, v[56:57], off
	s_nop 0
	global_load_dword v56, v[6:7], off offset:-4096
	s_nop 0
	global_load_dword v54, v[54:55], off
	s_nop 0
	global_load_dword v55, v[58:59], off
	v_add_co_u32_e32 v58, vcc, 0xffffc000, v6
	s_add_i32 s19, s19, 8
	s_nop 0
	v_addc_co_u32_e32 v59, vcc, -1, v7, vcc
	global_load_dword v62, v[62:63], off
	s_nop 0
	global_load_dword v63, v[58:59], off
	global_load_dword v57, v[6:7], off
	s_add_u32 s14, s14, 32
	s_addc_u32 s15, s15, 0
	v_lshl_add_u64 v[6:7], v[6:7], 0, s[44:45]
	s_waitcnt vmcnt(48)
	v_pk_mov_b32 v[122:123], v[90:91], v[98:99] op_sel:[1,0]
	v_mov_b32_e32 v91, v99
	v_mov_b32_e32 v98, v92
	v_mov_b32_e32 v99, v100
	v_mov_b32_e32 v100, v93
	v_pk_mov_b32 v[92:93], v[86:87], v[94:95] op_sel:[1,0]
	s_waitcnt vmcnt(42)
	v_pk_mul_f32 v[78:79], v[78:79], v[124:125]
	v_mov_b32_e32 v87, v95
	v_mov_b32_e32 v94, v88
	v_mul_f32_e32 v88, v79, v103
	v_pk_mul_f32 v[86:87], v[78:79], v[86:87]
	s_waitcnt vmcnt(39)
	v_pk_mul_f32 v[82:83], v[82:83], v[118:119]
	v_mov_b32_e32 v95, v96
	v_mov_b32_e32 v96, v89
	s_waitcnt vmcnt(36)
	v_pk_mul_f32 v[80:81], v[80:81], v[120:121]
	v_mul_f32_e32 v120, v78, v110
	v_pk_fma_f32 v[88:89], v[78:79], v[102:103], v[88:89] op_sel_hi:[1,1,0]
	v_pk_fma_f32 v[102:103], v[78:79], v[110:111], v[120:121] op_sel_hi:[1,1,0]
	v_pk_fma_f32 v[78:79], v[78:79], v[92:93], v[86:87] op_sel:[1,0,0] op_sel_hi:[0,1,1]
	v_mul_f32_e32 v86, v83, v107
	v_mul_f32_e32 v92, v82, v114
	v_pk_mul_f32 v[90:91], v[82:83], v[90:91]
	v_pk_fma_f32 v[86:87], v[82:83], v[106:107], v[86:87] op_sel_hi:[1,1,0]
	v_pk_fma_f32 v[92:93], v[82:83], v[114:115], v[92:93] op_sel_hi:[1,1,0]
	v_pk_mul_f32 v[84:85], v[84:85], v[126:127]
	v_pk_fma_f32 v[82:83], v[82:83], v[122:123], v[90:91] op_sel:[1,0,0] op_sel_hi:[0,1,1]
	v_pk_mul_f32 v[112:113], v[80:81], v[112:113]
	v_pk_fma_f32 v[82:83], v[84:85], v[98:99], v[82:83] op_sel_hi:[0,1,1]
	v_pk_mul_f32 v[90:91], v[84:85], v[116:117]
	v_pk_fma_f32 v[78:79], v[80:81], v[94:95], v[78:79] op_sel_hi:[0,1,1]
	v_mul_f32_e32 v102, v80, v104
	v_mov_b32_e32 v89, v112
	v_mul_f32_e32 v92, v84, v108
	v_pk_fma_f32 v[82:83], v[84:85], v[100:101], v[82:83] op_sel:[1,0,0]
	v_mov_b32_e32 v87, v90
	v_mul_f32_e32 v124, v81, v105
	v_pk_fma_f32 v[78:79], v[80:81], v[96:97], v[78:79] op_sel:[1,0,0]
	v_pk_add_f32 v[80:81], v[88:89], v[102:103]
	v_mul_f32_e32 v88, v85, v109
	v_mov_b32_e32 v89, v91
	v_pk_add_f32 v[4:5], v[4:5], v[82:83]
	v_pk_add_f32 v[82:83], v[86:87], v[92:93]
	v_mov_b32_e32 v125, v113
	v_pk_add_f32 v[82:83], v[88:89], v[82:83]
	v_pk_add_f32 v[80:81], v[124:125], v[80:81]
	v_pk_add_f32 v[10:11], v[10:11], v[82:83]
	v_pk_add_f32 v[4:5], v[4:5], v[78:79]
	v_pk_add_f32 v[10:11], v[10:11], v[80:81]
	v_add_co_u32_e32 v118, vcc, 0xffff9000, v6
	v_lshl_add_u64 v[82:83], v[8:9], 0, s[14:15]
	s_nop 0
	v_addc_co_u32_e32 v119, vcc, -1, v7, vcc
	v_add_co_u32_e32 v122, vcc, 0xffffa000, v6
	v_lshl_add_u64 v[114:115], v[12:13], 0, s[14:15]
	s_nop 0
	v_addc_co_u32_e32 v123, vcc, -1, v7, vcc
;     ...
;     const float* pw = pool_w + (size_t)(g * 128 + (kb & 127)) * 128;
; #pragma unroll 2
;     for (int d = 0; d < 128; d += 4) {
;       const f32x4 ps = *(const f32x4*)(pool_s + g * 128 + d);
;       float wv[4];
;       for (int q = 0; q < 4; ++q) wv[q] = ps[q] * w_branch[(long)(g * 128 + d + q) * DM + n];
;       for (int jj = 0; jj < 4; ++jj) {
;         const f32x4 p4 = *(const f32x4*)(pw + jj * 128 + d);
;         accv[jj] += p4[0] * wv[0] + p4[1] * wv[1] + p4[2] * wv[2] + p4[3] * wv[3];
;       }
;     }
	v_add_co_u32_e32 v126, vcc, 0xffffb000, v6
	v_add_co_u32_e64 v120, s[8:9], s21, v6
	s_nop 0
	v_addc_co_u32_e32 v127, vcc, -1, v7, vcc
	v_addc_co_u32_e64 v121, s[8:9], -1, v7, s[8:9]
	global_load_dwordx4 v[78:81], v[82:83], off
	s_nop 0
	global_load_dwordx4 v[82:85], v[82:83], off offset:-16
	s_nop 0
	global_load_dwordx4 v[86:89], v[114:115], off offset:16
	global_load_dwordx4 v[90:93], v[114:115], off
	global_load_dwordx4 v[94:97], v[114:115], off offset:528
	global_load_dwordx4 v[98:101], v[114:115], off offset:512
	global_load_dwordx4 v[102:105], v[114:115], off offset:1040
	global_load_dwordx4 v[106:109], v[114:115], off offset:1024
	global_load_dwordx4 v[110:113], v[114:115], off offset:1552
	s_nop 0
	global_load_dwordx4 v[114:117], v[114:115], off offset:1536
	s_nop 0
	global_load_dword v124, v[120:121], off offset:-4096
	global_load_dword v125, v[120:121], off
	s_nop 0
	global_load_dword v120, v[6:7], off offset:-4096
	s_nop 0
	global_load_dword v118, v[118:119], off
	s_nop 0
	global_load_dword v119, v[122:123], off
	v_add_co_u32_e32 v122, vcc, 0xffffc000, v6
	s_add_i32 s19, s19, 8
	s_nop 0
	v_addc_co_u32_e32 v123, vcc, -1, v7, vcc
	global_load_dword v126, v[126:127], off
	s_nop 0
	global_load_dword v127, v[122:123], off
	global_load_dword v121, v[6:7], off
	s_add_u32 s14, s14, 32
	s_addc_u32 s15, s15, 0
	v_lshl_add_u64 v[6:7], v[6:7], 0, s[44:45]
	s_waitcnt vmcnt(48)
	v_pk_mov_b32 v[186:187], v[154:155], v[162:163] op_sel:[1,0]
	v_mov_b32_e32 v155, v163
	v_mov_b32_e32 v162, v156
	v_mov_b32_e32 v163, v164
	v_mov_b32_e32 v164, v157
	v_pk_mov_b32 v[156:157], v[150:151], v[158:159] op_sel:[1,0]
	s_waitcnt vmcnt(42)
	v_pk_mul_f32 v[142:143], v[142:143], v[188:189]
	v_mov_b32_e32 v151, v159
	v_mov_b32_e32 v158, v152
	v_mul_f32_e32 v152, v143, v167
	v_pk_mul_f32 v[150:151], v[142:143], v[150:151]
	s_waitcnt vmcnt(39)
	v_pk_mul_f32 v[146:147], v[146:147], v[182:183]
	v_mov_b32_e32 v159, v160
	v_mov_b32_e32 v160, v153
	s_waitcnt vmcnt(36)
	v_pk_mul_f32 v[144:145], v[144:145], v[184:185]
	v_mul_f32_e32 v184, v142, v174
	v_pk_fma_f32 v[152:153], v[142:143], v[166:167], v[152:153] op_sel_hi:[1,1,0]
	v_pk_fma_f32 v[166:167], v[142:143], v[174:175], v[184:185] op_sel_hi:[1,1,0]
	v_pk_fma_f32 v[142:143], v[142:143], v[156:157], v[150:151] op_sel:[1,0,0] op_sel_hi:[0,1,1]
	v_mul_f32_e32 v150, v147, v171
	v_mul_f32_e32 v156, v146, v178
	v_pk_mul_f32 v[154:155], v[146:147], v[154:155]
	v_pk_fma_f32 v[150:151], v[146:147], v[170:171], v[150:151] op_sel_hi:[1,1,0]
	v_pk_fma_f32 v[156:157], v[146:147], v[178:179], v[156:157] op_sel_hi:[1,1,0]
	v_pk_mul_f32 v[148:149], v[148:149], v[190:191]
	v_pk_fma_f32 v[146:147], v[146:147], v[186:187], v[154:155] op_sel:[1,0,0] op_sel_hi:[0,1,1]
	v_pk_mul_f32 v[176:177], v[144:145], v[176:177]
	v_pk_fma_f32 v[146:147], v[148:149], v[162:163], v[146:147] op_sel_hi:[0,1,1]
	v_pk_mul_f32 v[154:155], v[148:149], v[180:181]
	v_pk_fma_f32 v[142:143], v[144:145], v[158:159], v[142:143] op_sel_hi:[0,1,1]
	v_mul_f32_e32 v166, v144, v168
	v_mov_b32_e32 v153, v176
	v_mul_f32_e32 v156, v148, v172
	v_pk_fma_f32 v[146:147], v[148:149], v[164:165], v[146:147] op_sel:[1,0,0]
	v_mov_b32_e32 v151, v154
	v_mul_f32_e32 v188, v145, v169
	v_pk_fma_f32 v[142:143], v[144:145], v[160:161], v[142:143] op_sel:[1,0,0]
	v_pk_add_f32 v[144:145], v[152:153], v[166:167]
	v_mul_f32_e32 v152, v149, v173
	v_mov_b32_e32 v153, v155
	v_pk_add_f32 v[4:5], v[4:5], v[146:147]
	v_pk_add_f32 v[146:147], v[150:151], v[156:157]
	v_mov_b32_e32 v189, v177
	v_pk_add_f32 v[146:147], v[152:153], v[146:147]
	v_pk_add_f32 v[144:145], v[188:189], v[144:145]
	v_pk_add_f32 v[10:11], v[10:11], v[146:147]
	v_pk_add_f32 v[4:5], v[4:5], v[142:143]
	v_pk_add_f32 v[10:11], v[10:11], v[144:145]
	v_add_co_u32_e32 v182, vcc, 0xffff9000, v6
	v_lshl_add_u64 v[146:147], v[8:9], 0, s[14:15]
	s_nop 0
	v_addc_co_u32_e32 v183, vcc, -1, v7, vcc
	v_add_co_u32_e32 v186, vcc, 0xffffa000, v6
	v_lshl_add_u64 v[178:179], v[12:13], 0, s[14:15]
	s_nop 0
	v_addc_co_u32_e32 v187, vcc, -1, v7, vcc
	v_add_co_u32_e32 v190, vcc, 0xffffb000, v6
	v_add_co_u32_e64 v184, s[8:9], s21, v6
	s_nop 0
	v_addc_co_u32_e32 v191, vcc, -1, v7, vcc
	v_addc_co_u32_e64 v185, s[8:9], -1, v7, s[8:9]
	global_load_dwordx4 v[142:145], v[146:147], off
	s_nop 0
	global_load_dwordx4 v[146:149], v[146:147], off offset:-16
	s_nop 0
	global_load_dwordx4 v[150:153], v[178:179], off offset:16
	global_load_dwordx4 v[154:157], v[178:179], off
	global_load_dwordx4 v[158:161], v[178:179], off offset:528
	global_load_dwordx4 v[162:165], v[178:179], off offset:512
	global_load_dwordx4 v[166:169], v[178:179], off offset:1040
	global_load_dwordx4 v[170:173], v[178:179], off offset:1024
	global_load_dwordx4 v[174:177], v[178:179], off offset:1552
	s_nop 0
	global_load_dwordx4 v[178:181], v[178:179], off offset:1536
	s_nop 0
	global_load_dword v188, v[184:185], off offset:-4096
	global_load_dword v189, v[184:185], off
	s_nop 0
	global_load_dword v184, v[6:7], off offset:-4096
	s_nop 0
	global_load_dword v182, v[182:183], off
	s_nop 0
	global_load_dword v183, v[186:187], off
	v_add_co_u32_e32 v186, vcc, 0xffffc000, v6
	s_add_i32 s19, s19, 8
	s_nop 0
	v_addc_co_u32_e32 v187, vcc, -1, v7, vcc
	global_load_dword v190, v[190:191], off
	s_nop 0
	global_load_dword v191, v[186:187], off
	global_load_dword v185, v[6:7], off
	s_add_u32 s14, s14, 32
	s_addc_u32 s15, s15, 0
	v_lshl_add_u64 v[6:7], v[6:7], 0, s[44:45]
	s_waitcnt vmcnt(48)
	v_pk_mov_b32 v[58:59], v[26:27], v[34:35] op_sel:[1,0]
	v_mov_b32_e32 v27, v35
	v_mov_b32_e32 v34, v28
	v_mov_b32_e32 v35, v36
	v_mov_b32_e32 v36, v29
	v_pk_mov_b32 v[28:29], v[22:23], v[30:31] op_sel:[1,0]
	s_waitcnt vmcnt(42)
;     ...
;     const float* pw = pool_w + (size_t)(g * 128 + (kb & 127)) * 128;
; #pragma unroll 2
;     for (int d = 0; d < 128; d += 4) {
;       const f32x4 ps = *(const f32x4*)(pool_s + g * 128 + d);
;       float wv[4];
;       for (int q = 0; q < 4; ++q) wv[q] = ps[q] * w_branch[(long)(g * 128 + d + q) * DM + n];
;       for (int jj = 0; jj < 4; ++jj) {
;         const f32x4 p4 = *(const f32x4*)(pw + jj * 128 + d);
;         accv[jj] += p4[0] * wv[0] + p4[1] * wv[1] + p4[2] * wv[2] + p4[3] * wv[3];
;       }
;     }
	v_pk_mul_f32 v[14:15], v[14:15], v[60:61]
	v_mov_b32_e32 v23, v31
	v_mov_b32_e32 v30, v24
	v_mul_f32_e32 v24, v15, v39
	v_pk_mul_f32 v[22:23], v[14:15], v[22:23]
	s_waitcnt vmcnt(39)
	v_pk_mul_f32 v[18:19], v[18:19], v[54:55]
	v_mov_b32_e32 v31, v32
	v_mov_b32_e32 v32, v25
	s_waitcnt vmcnt(36)
	v_pk_mul_f32 v[16:17], v[16:17], v[56:57]
	v_mul_f32_e32 v56, v14, v46
	v_pk_fma_f32 v[24:25], v[14:15], v[38:39], v[24:25] op_sel_hi:[1,1,0]
	v_pk_fma_f32 v[38:39], v[14:15], v[46:47], v[56:57] op_sel_hi:[1,1,0]
	v_pk_fma_f32 v[14:15], v[14:15], v[28:29], v[22:23] op_sel:[1,0,0] op_sel_hi:[0,1,1]
	v_mul_f32_e32 v22, v19, v43
	v_mul_f32_e32 v28, v18, v50
	v_pk_mul_f32 v[26:27], v[18:19], v[26:27]
	v_pk_fma_f32 v[22:23], v[18:19], v[42:43], v[22:23] op_sel_hi:[1,1,0]
	v_pk_fma_f32 v[28:29], v[18:19], v[50:51], v[28:29] op_sel_hi:[1,1,0]
	v_pk_mul_f32 v[20:21], v[20:21], v[62:63]
	v_pk_fma_f32 v[18:19], v[18:19], v[58:59], v[26:27] op_sel:[1,0,0] op_sel_hi:[0,1,1]
	v_pk_mul_f32 v[48:49], v[16:17], v[48:49]
	v_pk_fma_f32 v[18:19], v[20:21], v[34:35], v[18:19] op_sel_hi:[0,1,1]
	v_pk_mul_f32 v[26:27], v[20:21], v[52:53]
	v_pk_fma_f32 v[14:15], v[16:17], v[30:31], v[14:15] op_sel_hi:[0,1,1]
	v_mul_f32_e32 v38, v16, v40
	v_mov_b32_e32 v25, v48
	v_mul_f32_e32 v28, v20, v44
	v_pk_fma_f32 v[18:19], v[20:21], v[36:37], v[18:19] op_sel:[1,0,0]
	v_mov_b32_e32 v23, v26
	v_mul_f32_e32 v60, v17, v41
	v_pk_fma_f32 v[14:15], v[16:17], v[32:33], v[14:15] op_sel:[1,0,0]
	v_pk_add_f32 v[16:17], v[24:25], v[38:39]
	v_mul_f32_e32 v24, v21, v45
	v_mov_b32_e32 v25, v27
	v_pk_add_f32 v[4:5], v[4:5], v[18:19]
	v_pk_add_f32 v[18:19], v[22:23], v[28:29]
	v_mov_b32_e32 v61, v49
	v_pk_add_f32 v[18:19], v[24:25], v[18:19]
	v_pk_add_f32 v[16:17], v[60:61], v[16:17]
	v_pk_add_f32 v[10:11], v[10:11], v[18:19]
	v_pk_add_f32 v[4:5], v[4:5], v[14:15]
	v_pk_add_f32 v[10:11], v[10:11], v[16:17]
	v_add_co_u32_e32 v54, vcc, 0xffff9000, v6
	v_lshl_add_u64 v[18:19], v[8:9], 0, s[14:15]
	s_nop 0
	v_addc_co_u32_e32 v55, vcc, -1, v7, vcc
	v_add_co_u32_e32 v58, vcc, 0xffffa000, v6
	v_lshl_add_u64 v[50:51], v[12:13], 0, s[14:15]
	s_nop 0
	v_addc_co_u32_e32 v59, vcc, -1, v7, vcc
	v_add_co_u32_e32 v62, vcc, 0xffffb000, v6
	v_add_co_u32_e64 v56, s[8:9], s21, v6
	s_nop 0
	v_addc_co_u32_e32 v63, vcc, -1, v7, vcc
	v_addc_co_u32_e64 v57, s[8:9], -1, v7, s[8:9]
	global_load_dwordx4 v[14:17], v[18:19], off
	s_nop 0
	global_load_dwordx4 v[18:21], v[18:19], off offset:-16
	s_nop 0
	global_load_dwordx4 v[22:25], v[50:51], off offset:16
	global_load_dwordx4 v[26:29], v[50:51], off
	global_load_dwordx4 v[30:33], v[50:51], off offset:528
	global_load_dwordx4 v[34:37], v[50:51], off offset:512
	global_load_dwordx4 v[38:41], v[50:51], off offset:1040
	global_load_dwordx4 v[42:45], v[50:51], off offset:1024
	global_load_dwordx4 v[46:49], v[50:51], off offset:1552
	s_nop 0
	global_load_dwordx4 v[50:53], v[50:51], off offset:1536
	s_nop 0
	global_load_dword v60, v[56:57], off offset:-4096
	global_load_dword v61, v[56:57], off
	s_nop 0
	global_load_dword v56, v[6:7], off offset:-4096
	s_nop 0
	global_load_dword v54, v[54:55], off
	s_nop 0
	global_load_dword v55, v[58:59], off
	v_add_co_u32_e32 v58, vcc, 0xffffc000, v6
	s_add_i32 s19, s19, 8
	s_nop 0
	v_addc_co_u32_e32 v59, vcc, -1, v7, vcc
	global_load_dword v62, v[62:63], off
	s_nop 0
	global_load_dword v63, v[58:59], off
	global_load_dword v57, v[6:7], off
	s_add_u32 s14, s14, 32
	s_addc_u32 s15, s15, 0
	v_lshl_add_u64 v[6:7], v[6:7], 0, s[44:45]
	s_waitcnt vmcnt(48)
	v_pk_mov_b32 v[122:123], v[90:91], v[98:99] op_sel:[1,0]
	v_mov_b32_e32 v91, v99
	v_mov_b32_e32 v98, v92
	v_mov_b32_e32 v99, v100
	v_mov_b32_e32 v100, v93
	v_pk_mov_b32 v[92:93], v[86:87], v[94:95] op_sel:[1,0]
	s_waitcnt vmcnt(42)
	v_pk_mul_f32 v[78:79], v[78:79], v[124:125]
	v_mov_b32_e32 v87, v95
	v_mov_b32_e32 v94, v88
	v_mul_f32_e32 v88, v79, v103
	v_pk_mul_f32 v[86:87], v[78:79], v[86:87]
	s_waitcnt vmcnt(39)
	v_pk_mul_f32 v[82:83], v[82:83], v[118:119]
	v_mov_b32_e32 v95, v96
	v_mov_b32_e32 v96, v89
	s_waitcnt vmcnt(36)
	v_pk_mul_f32 v[80:81], v[80:81], v[120:121]
	v_mul_f32_e32 v120, v78, v110
	v_pk_fma_f32 v[88:89], v[78:79], v[102:103], v[88:89] op_sel_hi:[1,1,0]
	v_pk_fma_f32 v[102:103], v[78:79], v[110:111], v[120:121] op_sel_hi:[1,1,0]
	v_pk_fma_f32 v[78:79], v[78:79], v[92:93], v[86:87] op_sel:[1,0,0] op_sel_hi:[0,1,1]
	v_mul_f32_e32 v86, v83, v107
	v_mul_f32_e32 v92, v82, v114
	v_pk_mul_f32 v[90:91], v[82:83], v[90:91]
	v_pk_fma_f32 v[86:87], v[82:83], v[106:107], v[86:87] op_sel_hi:[1,1,0]
	v_pk_fma_f32 v[92:93], v[82:83], v[114:115], v[92:93] op_sel_hi:[1,1,0]
	v_pk_mul_f32 v[84:85], v[84:85], v[126:127]
	v_pk_fma_f32 v[82:83], v[82:83], v[122:123], v[90:91] op_sel:[1,0,0] op_sel_hi:[0,1,1]
	v_pk_mul_f32 v[112:113], v[80:81], v[112:113]
	v_pk_fma_f32 v[82:83], v[84:85], v[98:99], v[82:83] op_sel_hi:[0,1,1]
	v_pk_mul_f32 v[90:91], v[84:85], v[116:117]
	v_pk_fma_f32 v[78:79], v[80:81], v[94:95], v[78:79] op_sel_hi:[0,1,1]
	v_mul_f32_e32 v102, v80, v104
	v_mov_b32_e32 v89, v112
	v_mul_f32_e32 v92, v84, v108
	v_pk_fma_f32 v[82:83], v[84:85], v[100:101], v[82:83] op_sel:[1,0,0]
	v_mov_b32_e32 v87, v90
	v_mul_f32_e32 v124, v81, v105
	v_pk_fma_f32 v[78:79], v[80:81], v[96:97], v[78:79] op_sel:[1,0,0]
	v_pk_add_f32 v[80:81], v[88:89], v[102:103]
	v_mul_f32_e32 v88, v85, v109
	v_mov_b32_e32 v89, v91
	v_pk_add_f32 v[4:5], v[4:5], v[82:83]
	v_pk_add_f32 v[82:83], v[86:87], v[92:93]
	v_mov_b32_e32 v125, v113
	v_pk_add_f32 v[82:83], v[88:89], v[82:83]
	v_pk_add_f32 v[80:81], v[124:125], v[80:81]
	v_pk_add_f32 v[10:11], v[10:11], v[82:83]
	v_pk_add_f32 v[4:5], v[4:5], v[78:79]
;     ...
;     const float* pw = pool_w + (size_t)(g * 128 + (kb & 127)) * 128;
; #pragma unroll 2
;     for (int d = 0; d < 128; d += 4) {
;       const f32x4 ps = *(const f32x4*)(pool_s + g * 128 + d);
;       float wv[4];
;       for (int q = 0; q < 4; ++q) wv[q] = ps[q] * w_branch[(long)(g * 128 + d + q) * DM + n];
;       for (int jj = 0; jj < 4; ++jj) {
;         const f32x4 p4 = *(const f32x4*)(pw + jj * 128 + d);
;         accv[jj] += p4[0] * wv[0] + p4[1] * wv[1] + p4[2] * wv[2] + p4[3] * wv[3];
;       }
;     }
	v_pk_add_f32 v[10:11], v[10:11], v[80:81]
	v_add_co_u32_e32 v118, vcc, 0xffff9000, v6
	v_lshl_add_u64 v[82:83], v[8:9], 0, s[14:15]
	s_nop 0
	v_addc_co_u32_e32 v119, vcc, -1, v7, vcc
	v_add_co_u32_e32 v122, vcc, 0xffffa000, v6
	v_lshl_add_u64 v[114:115], v[12:13], 0, s[14:15]
	s_nop 0
	v_addc_co_u32_e32 v123, vcc, -1, v7, vcc
	v_add_co_u32_e32 v126, vcc, 0xffffb000, v6
	v_add_co_u32_e64 v120, s[8:9], s21, v6
	s_nop 0
	v_addc_co_u32_e32 v127, vcc, -1, v7, vcc
	v_addc_co_u32_e64 v121, s[8:9], -1, v7, s[8:9]
	global_load_dwordx4 v[78:81], v[82:83], off
	s_nop 0
	global_load_dwordx4 v[82:85], v[82:83], off offset:-16
	s_nop 0
	global_load_dwordx4 v[86:89], v[114:115], off offset:16
	global_load_dwordx4 v[90:93], v[114:115], off
	global_load_dwordx4 v[94:97], v[114:115], off offset:528
	global_load_dwordx4 v[98:101], v[114:115], off offset:512
	global_load_dwordx4 v[102:105], v[114:115], off offset:1040
	global_load_dwordx4 v[106:109], v[114:115], off offset:1024
	global_load_dwordx4 v[110:113], v[114:115], off offset:1552
	s_nop 0
	global_load_dwordx4 v[114:117], v[114:115], off offset:1536
	s_nop 0
	global_load_dword v124, v[120:121], off offset:-4096
	global_load_dword v125, v[120:121], off
	s_nop 0
	global_load_dword v120, v[6:7], off offset:-4096
	s_nop 0
	global_load_dword v118, v[118:119], off
	s_nop 0
	global_load_dword v119, v[122:123], off
	v_add_co_u32_e32 v122, vcc, 0xffffc000, v6
	s_add_i32 s19, s19, 8
	s_nop 0
	v_addc_co_u32_e32 v123, vcc, -1, v7, vcc
	global_load_dword v126, v[126:127], off
	s_nop 0
	global_load_dword v127, v[122:123], off
	global_load_dword v121, v[6:7], off
	s_add_u32 s14, s14, 32
	s_addc_u32 s15, s15, 0
	v_lshl_add_u64 v[6:7], v[6:7], 0, s[44:45]
	s_waitcnt vmcnt(48)
	v_pk_mov_b32 v[186:187], v[154:155], v[162:163] op_sel:[1,0]
	v_mov_b32_e32 v155, v163
	v_mov_b32_e32 v162, v156
	v_mov_b32_e32 v163, v164
	v_mov_b32_e32 v164, v157
	v_pk_mov_b32 v[156:157], v[150:151], v[158:159] op_sel:[1,0]
	s_waitcnt vmcnt(42)
	v_pk_mul_f32 v[142:143], v[142:143], v[188:189]
	v_mov_b32_e32 v151, v159
	v_mov_b32_e32 v158, v152
	v_mul_f32_e32 v152, v143, v167
	v_pk_mul_f32 v[150:151], v[142:143], v[150:151]
	s_waitcnt vmcnt(39)
	v_pk_mul_f32 v[146:147], v[146:147], v[182:183]
	v_mov_b32_e32 v159, v160
	v_mov_b32_e32 v160, v153
	s_waitcnt vmcnt(36)
	v_pk_mul_f32 v[144:145], v[144:145], v[184:185]
	v_mul_f32_e32 v184, v142, v174
	v_pk_fma_f32 v[152:153], v[142:143], v[166:167], v[152:153] op_sel_hi:[1,1,0]
	v_pk_fma_f32 v[166:167], v[142:143], v[174:175], v[184:185] op_sel_hi:[1,1,0]
	v_pk_fma_f32 v[142:143], v[142:143], v[156:157], v[150:151] op_sel:[1,0,0] op_sel_hi:[0,1,1]
	v_mul_f32_e32 v150, v147, v171
	v_mul_f32_e32 v156, v146, v178
	v_pk_mul_f32 v[154:155], v[146:147], v[154:155]
	v_pk_fma_f32 v[150:151], v[146:147], v[170:171], v[150:151] op_sel_hi:[1,1,0]
	v_pk_fma_f32 v[156:157], v[146:147], v[178:179], v[156:157] op_sel_hi:[1,1,0]
	v_pk_mul_f32 v[148:149], v[148:149], v[190:191]
	v_pk_fma_f32 v[146:147], v[146:147], v[186:187], v[154:155] op_sel:[1,0,0] op_sel_hi:[0,1,1]
	v_pk_mul_f32 v[176:177], v[144:145], v[176:177]
	v_pk_fma_f32 v[146:147], v[148:149], v[162:163], v[146:147] op_sel_hi:[0,1,1]
	v_pk_mul_f32 v[154:155], v[148:149], v[180:181]
	v_pk_fma_f32 v[142:143], v[144:145], v[158:159], v[142:143] op_sel_hi:[0,1,1]
	v_mul_f32_e32 v166, v144, v168
	v_mov_b32_e32 v153, v176
	v_mul_f32_e32 v156, v148, v172
	v_pk_fma_f32 v[146:147], v[148:149], v[164:165], v[146:147] op_sel:[1,0,0]
	v_mov_b32_e32 v151, v154
	v_mul_f32_e32 v188, v145, v169
	v_pk_fma_f32 v[142:143], v[144:145], v[160:161], v[142:143] op_sel:[1,0,0]
	v_pk_add_f32 v[144:145], v[152:153], v[166:167]
	v_mul_f32_e32 v152, v149, v173
	v_mov_b32_e32 v153, v155
	v_pk_add_f32 v[4:5], v[4:5], v[146:147]
	v_pk_add_f32 v[146:147], v[150:151], v[156:157]
	v_mov_b32_e32 v189, v177
	v_pk_add_f32 v[146:147], v[152:153], v[146:147]
	v_pk_add_f32 v[144:145], v[188:189], v[144:145]
	v_pk_add_f32 v[10:11], v[10:11], v[146:147]
	v_pk_add_f32 v[4:5], v[4:5], v[142:143]
	v_pk_add_f32 v[10:11], v[10:11], v[144:145]
	v_add_co_u32_e32 v182, vcc, 0xffff9000, v6
	v_lshl_add_u64 v[146:147], v[8:9], 0, s[14:15]
	s_nop 0
	v_addc_co_u32_e32 v183, vcc, -1, v7, vcc
	v_add_co_u32_e32 v186, vcc, 0xffffa000, v6
	v_lshl_add_u64 v[178:179], v[12:13], 0, s[14:15]
	s_nop 0
	v_addc_co_u32_e32 v187, vcc, -1, v7, vcc
	v_add_co_u32_e32 v190, vcc, 0xffffb000, v6
	v_add_co_u32_e64 v184, s[8:9], s21, v6
	s_nop 0
	v_addc_co_u32_e32 v191, vcc, -1, v7, vcc
	v_addc_co_u32_e64 v185, s[8:9], -1, v7, s[8:9]
	global_load_dwordx4 v[142:145], v[146:147], off
	s_nop 0
	global_load_dwordx4 v[146:149], v[146:147], off offset:-16
	s_nop 0
	global_load_dwordx4 v[150:153], v[178:179], off offset:16
	global_load_dwordx4 v[154:157], v[178:179], off
	global_load_dwordx4 v[158:161], v[178:179], off offset:528
	global_load_dwordx4 v[162:165], v[178:179], off offset:512
	global_load_dwordx4 v[166:169], v[178:179], off offset:1040
	global_load_dwordx4 v[170:173], v[178:179], off offset:1024
	global_load_dwordx4 v[174:177], v[178:179], off offset:1552
	s_nop 0
	global_load_dwordx4 v[178:181], v[178:179], off offset:1536
	s_nop 0
	global_load_dword v188, v[184:185], off offset:-4096
	global_load_dword v189, v[184:185], off
	s_nop 0
	global_load_dword v184, v[6:7], off offset:-4096
	s_nop 0
	global_load_dword v182, v[182:183], off
	s_nop 0
	global_load_dword v183, v[186:187], off
	v_add_co_u32_e32 v186, vcc, 0xffffc000, v6
	s_add_i32 s19, s19, 8
	s_nop 0
	v_addc_co_u32_e32 v187, vcc, -1, v7, vcc
	global_load_dword v190, v[190:191], off
	s_nop 0
	global_load_dword v191, v[186:187], off
	global_load_dword v185, v[6:7], off
	s_add_u32 s14, s14, 32
	s_addc_u32 s15, s15, 0
	v_lshl_add_u64 v[6:7], v[6:7], 0, s[44:45]
	s_waitcnt vmcnt(48)
;     ...
;     const float* pw = pool_w + (size_t)(g * 128 + (kb & 127)) * 128;
; #pragma unroll 2
;     for (int d = 0; d < 128; d += 4) {
;       const f32x4 ps = *(const f32x4*)(pool_s + g * 128 + d);
;       float wv[4];
;       for (int q = 0; q < 4; ++q) wv[q] = ps[q] * w_branch[(long)(g * 128 + d + q) * DM + n];
;       for (int jj = 0; jj < 4; ++jj) {
;         const f32x4 p4 = *(const f32x4*)(pw + jj * 128 + d);
;         accv[jj] += p4[0] * wv[0] + p4[1] * wv[1] + p4[2] * wv[2] + p4[3] * wv[3];
;       }
;     }
	v_pk_mov_b32 v[58:59], v[26:27], v[34:35] op_sel:[1,0]
	v_mov_b32_e32 v27, v35
	v_mov_b32_e32 v34, v28
	v_mov_b32_e32 v35, v36
	v_mov_b32_e32 v36, v29
	v_pk_mov_b32 v[28:29], v[22:23], v[30:31] op_sel:[1,0]
	s_waitcnt vmcnt(42)
	v_pk_mul_f32 v[14:15], v[14:15], v[60:61]
	v_mov_b32_e32 v23, v31
	v_mov_b32_e32 v30, v24
	v_mul_f32_e32 v24, v15, v39
	v_pk_mul_f32 v[22:23], v[14:15], v[22:23]
	s_waitcnt vmcnt(39)
	v_pk_mul_f32 v[18:19], v[18:19], v[54:55]
	v_mov_b32_e32 v31, v32
	v_mov_b32_e32 v32, v25
	s_waitcnt vmcnt(36)
	v_pk_mul_f32 v[16:17], v[16:17], v[56:57]
	v_mul_f32_e32 v56, v14, v46
	v_pk_fma_f32 v[24:25], v[14:15], v[38:39], v[24:25] op_sel_hi:[1,1,0]
	v_pk_fma_f32 v[38:39], v[14:15], v[46:47], v[56:57] op_sel_hi:[1,1,0]
	v_pk_fma_f32 v[14:15], v[14:15], v[28:29], v[22:23] op_sel:[1,0,0] op_sel_hi:[0,1,1]
	v_mul_f32_e32 v22, v19, v43
	v_mul_f32_e32 v28, v18, v50
	v_pk_mul_f32 v[26:27], v[18:19], v[26:27]
	v_pk_fma_f32 v[22:23], v[18:19], v[42:43], v[22:23] op_sel_hi:[1,1,0]
	v_pk_fma_f32 v[28:29], v[18:19], v[50:51], v[28:29] op_sel_hi:[1,1,0]
	v_pk_mul_f32 v[20:21], v[20:21], v[62:63]
	v_pk_fma_f32 v[18:19], v[18:19], v[58:59], v[26:27] op_sel:[1,0,0] op_sel_hi:[0,1,1]
	v_pk_mul_f32 v[48:49], v[16:17], v[48:49]
	v_pk_fma_f32 v[18:19], v[20:21], v[34:35], v[18:19] op_sel_hi:[0,1,1]
	v_pk_mul_f32 v[26:27], v[20:21], v[52:53]
	v_pk_fma_f32 v[14:15], v[16:17], v[30:31], v[14:15] op_sel_hi:[0,1,1]
	v_mul_f32_e32 v38, v16, v40
	v_mov_b32_e32 v25, v48
	v_mul_f32_e32 v28, v20, v44
	v_pk_fma_f32 v[18:19], v[20:21], v[36:37], v[18:19] op_sel:[1,0,0]
	v_mov_b32_e32 v23, v26
	v_mul_f32_e32 v60, v17, v41
	v_pk_fma_f32 v[14:15], v[16:17], v[32:33], v[14:15] op_sel:[1,0,0]
	v_pk_add_f32 v[16:17], v[24:25], v[38:39]
	v_mul_f32_e32 v24, v21, v45
	v_mov_b32_e32 v25, v27
	v_pk_add_f32 v[4:5], v[4:5], v[18:19]
	v_pk_add_f32 v[18:19], v[22:23], v[28:29]
	v_mov_b32_e32 v61, v49
	v_pk_add_f32 v[18:19], v[24:25], v[18:19]
	v_pk_add_f32 v[16:17], v[60:61], v[16:17]
	v_pk_add_f32 v[10:11], v[10:11], v[18:19]
	v_pk_add_f32 v[4:5], v[4:5], v[14:15]
	v_pk_add_f32 v[10:11], v[10:11], v[16:17]
	v_add_co_u32_e32 v54, vcc, 0xffff9000, v6
	v_lshl_add_u64 v[18:19], v[8:9], 0, s[14:15]
	s_nop 0
	v_addc_co_u32_e32 v55, vcc, -1, v7, vcc
	v_add_co_u32_e32 v58, vcc, 0xffffa000, v6
	v_lshl_add_u64 v[50:51], v[12:13], 0, s[14:15]
	s_nop 0
	v_addc_co_u32_e32 v59, vcc, -1, v7, vcc
	v_add_co_u32_e32 v62, vcc, 0xffffb000, v6
	v_add_co_u32_e64 v56, s[8:9], s21, v6
	s_nop 0
	v_addc_co_u32_e32 v63, vcc, -1, v7, vcc
	v_addc_co_u32_e64 v57, s[8:9], -1, v7, s[8:9]
	global_load_dwordx4 v[14:17], v[18:19], off
	s_nop 0
	global_load_dwordx4 v[18:21], v[18:19], off offset:-16
	s_nop 0
	global_load_dwordx4 v[22:25], v[50:51], off offset:16
	global_load_dwordx4 v[26:29], v[50:51], off
	global_load_dwordx4 v[30:33], v[50:51], off offset:528
	global_load_dwordx4 v[34:37], v[50:51], off offset:512
	global_load_dwordx4 v[38:41], v[50:51], off offset:1040
	global_load_dwordx4 v[42:45], v[50:51], off offset:1024
	global_load_dwordx4 v[46:49], v[50:51], off offset:1552
	s_nop 0
	global_load_dwordx4 v[50:53], v[50:51], off offset:1536
	s_nop 0
	global_load_dword v60, v[56:57], off offset:-4096
	global_load_dword v61, v[56:57], off
	s_nop 0
	global_load_dword v56, v[6:7], off offset:-4096
	s_nop 0
	global_load_dword v54, v[54:55], off
	s_nop 0
	global_load_dword v55, v[58:59], off
	v_add_co_u32_e32 v58, vcc, 0xffffc000, v6
	s_add_i32 s19, s19, 8
	s_nop 0
	v_addc_co_u32_e32 v59, vcc, -1, v7, vcc
	global_load_dword v62, v[62:63], off
	s_nop 0
	global_load_dword v63, v[58:59], off
	global_load_dword v57, v[6:7], off
	s_add_u32 s14, s14, 32
	s_addc_u32 s15, s15, 0
	v_lshl_add_u64 v[6:7], v[6:7], 0, s[44:45]
	s_waitcnt vmcnt(48)
	v_pk_mov_b32 v[122:123], v[90:91], v[98:99] op_sel:[1,0]
	v_mov_b32_e32 v91, v99
	v_mov_b32_e32 v98, v92
	v_mov_b32_e32 v99, v100
	v_mov_b32_e32 v100, v93
	v_pk_mov_b32 v[92:93], v[86:87], v[94:95] op_sel:[1,0]
	s_waitcnt vmcnt(42)
	v_pk_mul_f32 v[78:79], v[78:79], v[124:125]
	v_mov_b32_e32 v87, v95
	v_mov_b32_e32 v94, v88
	v_mul_f32_e32 v88, v79, v103
	v_pk_mul_f32 v[86:87], v[78:79], v[86:87]
	s_waitcnt vmcnt(39)
	v_pk_mul_f32 v[82:83], v[82:83], v[118:119]
	v_mov_b32_e32 v95, v96
	v_mov_b32_e32 v96, v89
	s_waitcnt vmcnt(36)
;     ...
;     const float* pw = pool_w + (size_t)(g * 128 + (kb & 127)) * 128;
; #pragma unroll 2
;     for (int d = 0; d < 128; d += 4) {
;       const f32x4 ps = *(const f32x4*)(pool_s + g * 128 + d);
;       float wv[4];
;       for (int q = 0; q < 4; ++q) wv[q] = ps[q] * w_branch[(long)(g * 128 + d + q) * DM + n];
;       for (int jj = 0; jj < 4; ++jj) {
;         const f32x4 p4 = *(const f32x4*)(pw + jj * 128 + d);
;         accv[jj] += p4[0] * wv[0] + p4[1] * wv[1] + p4[2] * wv[2] + p4[3] * wv[3];
;       }
;     }
	v_pk_mul_f32 v[80:81], v[80:81], v[120:121]
	v_mul_f32_e32 v120, v78, v110
	v_pk_fma_f32 v[88:89], v[78:79], v[102:103], v[88:89] op_sel_hi:[1,1,0]
	v_pk_fma_f32 v[102:103], v[78:79], v[110:111], v[120:121] op_sel_hi:[1,1,0]
	v_pk_fma_f32 v[78:79], v[78:79], v[92:93], v[86:87] op_sel:[1,0,0] op_sel_hi:[0,1,1]
	v_mul_f32_e32 v86, v83, v107
	v_mul_f32_e32 v92, v82, v114
	v_pk_mul_f32 v[90:91], v[82:83], v[90:91]
	v_pk_fma_f32 v[86:87], v[82:83], v[106:107], v[86:87] op_sel_hi:[1,1,0]
	v_pk_fma_f32 v[92:93], v[82:83], v[114:115], v[92:93] op_sel_hi:[1,1,0]
	v_pk_mul_f32 v[84:85], v[84:85], v[126:127]
	v_pk_fma_f32 v[82:83], v[82:83], v[122:123], v[90:91] op_sel:[1,0,0] op_sel_hi:[0,1,1]
	v_pk_mul_f32 v[112:113], v[80:81], v[112:113]
	v_pk_fma_f32 v[82:83], v[84:85], v[98:99], v[82:83] op_sel_hi:[0,1,1]
	v_pk_mul_f32 v[90:91], v[84:85], v[116:117]
	v_pk_fma_f32 v[78:79], v[80:81], v[94:95], v[78:79] op_sel_hi:[0,1,1]
	v_mul_f32_e32 v102, v80, v104
	v_mov_b32_e32 v89, v112
	v_mul_f32_e32 v92, v84, v108
	v_pk_fma_f32 v[82:83], v[84:85], v[100:101], v[82:83] op_sel:[1,0,0]
	v_mov_b32_e32 v87, v90
	v_mul_f32_e32 v124, v81, v105
	v_pk_fma_f32 v[78:79], v[80:81], v[96:97], v[78:79] op_sel:[1,0,0]
	v_pk_add_f32 v[80:81], v[88:89], v[102:103]
	v_mul_f32_e32 v88, v85, v109
	v_mov_b32_e32 v89, v91
	v_pk_add_f32 v[4:5], v[4:5], v[82:83]
	v_pk_add_f32 v[82:83], v[86:87], v[92:93]
	v_mov_b32_e32 v125, v113
	v_pk_add_f32 v[82:83], v[88:89], v[82:83]
	v_pk_add_f32 v[80:81], v[124:125], v[80:81]
	v_pk_add_f32 v[10:11], v[10:11], v[82:83]
	v_pk_add_f32 v[4:5], v[4:5], v[78:79]
	v_pk_add_f32 v[10:11], v[10:11], v[80:81]
	v_add_co_u32_e32 v118, vcc, 0xffff9000, v6
	v_lshl_add_u64 v[82:83], v[8:9], 0, s[14:15]
	s_nop 0
	v_addc_co_u32_e32 v119, vcc, -1, v7, vcc
	v_add_co_u32_e32 v122, vcc, 0xffffa000, v6
	v_lshl_add_u64 v[114:115], v[12:13], 0, s[14:15]
	s_nop 0
	v_addc_co_u32_e32 v123, vcc, -1, v7, vcc
	v_add_co_u32_e32 v126, vcc, 0xffffb000, v6
	v_add_co_u32_e64 v120, s[8:9], s21, v6
	s_nop 0
	v_addc_co_u32_e32 v127, vcc, -1, v7, vcc
	v_addc_co_u32_e64 v121, s[8:9], -1, v7, s[8:9]
	global_load_dwordx4 v[78:81], v[82:83], off
	s_nop 0
	global_load_dwordx4 v[82:85], v[82:83], off offset:-16
	s_nop 0
	global_load_dwordx4 v[86:89], v[114:115], off offset:16
	global_load_dwordx4 v[90:93], v[114:115], off
	global_load_dwordx4 v[94:97], v[114:115], off offset:528
	global_load_dwordx4 v[98:101], v[114:115], off offset:512
	global_load_dwordx4 v[102:105], v[114:115], off offset:1040
	global_load_dwordx4 v[106:109], v[114:115], off offset:1024
	global_load_dwordx4 v[110:113], v[114:115], off offset:1552
	s_nop 0
	global_load_dwordx4 v[114:117], v[114:115], off offset:1536
	s_nop 0
	global_load_dword v124, v[120:121], off offset:-4096
	global_load_dword v125, v[120:121], off
	s_nop 0
	global_load_dword v120, v[6:7], off offset:-4096
	s_nop 0
	global_load_dword v118, v[118:119], off
	s_nop 0
	global_load_dword v119, v[122:123], off
	v_add_co_u32_e32 v122, vcc, 0xffffc000, v6
	s_add_i32 s19, s19, 8
	s_nop 0
	v_addc_co_u32_e32 v123, vcc, -1, v7, vcc
	global_load_dword v126, v[126:127], off
	s_nop 0
	global_load_dword v127, v[122:123], off
	global_load_dword v121, v[6:7], off
	s_add_u32 s14, s14, 32
	s_addc_u32 s15, s15, 0
	v_lshl_add_u64 v[6:7], v[6:7], 0, s[44:45]
	s_waitcnt vmcnt(48)
	v_pk_mov_b32 v[186:187], v[154:155], v[162:163] op_sel:[1,0]
	v_mov_b32_e32 v155, v163
	v_mov_b32_e32 v162, v156
	v_mov_b32_e32 v163, v164
	v_mov_b32_e32 v164, v157
	v_pk_mov_b32 v[156:157], v[150:151], v[158:159] op_sel:[1,0]
	s_waitcnt vmcnt(42)
	v_pk_mul_f32 v[142:143], v[142:143], v[188:189]
	v_mov_b32_e32 v151, v159
	v_mov_b32_e32 v158, v152
	v_mul_f32_e32 v152, v143, v167
	v_pk_mul_f32 v[150:151], v[142:143], v[150:151]
	s_waitcnt vmcnt(39)
	v_pk_mul_f32 v[146:147], v[146:147], v[182:183]
	v_mov_b32_e32 v159, v160
	v_mov_b32_e32 v160, v153
	s_waitcnt vmcnt(36)
	v_pk_mul_f32 v[144:145], v[144:145], v[184:185]
	v_mul_f32_e32 v184, v142, v174
	v_pk_fma_f32 v[152:153], v[142:143], v[166:167], v[152:153] op_sel_hi:[1,1,0]
	v_pk_fma_f32 v[166:167], v[142:143], v[174:175], v[184:185] op_sel_hi:[1,1,0]
	v_pk_fma_f32 v[142:143], v[142:143], v[156:157], v[150:151] op_sel:[1,0,0] op_sel_hi:[0,1,1]
	v_mul_f32_e32 v150, v147, v171
	v_mul_f32_e32 v156, v146, v178
	v_pk_mul_f32 v[154:155], v[146:147], v[154:155]
	v_pk_fma_f32 v[150:151], v[146:147], v[170:171], v[150:151] op_sel_hi:[1,1,0]
	v_pk_fma_f32 v[156:157], v[146:147], v[178:179], v[156:157] op_sel_hi:[1,1,0]
	v_pk_mul_f32 v[148:149], v[148:149], v[190:191]
	v_pk_fma_f32 v[146:147], v[146:147], v[186:187], v[154:155] op_sel:[1,0,0] op_sel_hi:[0,1,1]
	v_pk_mul_f32 v[176:177], v[144:145], v[176:177]
	v_pk_fma_f32 v[146:147], v[148:149], v[162:163], v[146:147] op_sel_hi:[0,1,1]
	v_pk_mul_f32 v[154:155], v[148:149], v[180:181]
	v_pk_fma_f32 v[142:143], v[144:145], v[158:159], v[142:143] op_sel_hi:[0,1,1]
	v_mul_f32_e32 v166, v144, v168
	v_mov_b32_e32 v153, v176
	v_mul_f32_e32 v156, v148, v172
	v_pk_fma_f32 v[146:147], v[148:149], v[164:165], v[146:147] op_sel:[1,0,0]
	v_mov_b32_e32 v151, v154
	v_mul_f32_e32 v188, v145, v169
	v_pk_fma_f32 v[142:143], v[144:145], v[160:161], v[142:143] op_sel:[1,0,0]
	v_pk_add_f32 v[144:145], v[152:153], v[166:167]
	v_mul_f32_e32 v152, v149, v173
	v_mov_b32_e32 v153, v155
	v_pk_add_f32 v[4:5], v[4:5], v[146:147]
	v_pk_add_f32 v[146:147], v[150:151], v[156:157]
	v_mov_b32_e32 v189, v177
	v_pk_add_f32 v[146:147], v[152:153], v[146:147]
	v_pk_add_f32 v[144:145], v[188:189], v[144:145]
	v_pk_add_f32 v[10:11], v[10:11], v[146:147]
	v_pk_add_f32 v[4:5], v[4:5], v[142:143]
	v_pk_add_f32 v[10:11], v[10:11], v[144:145]
;     ...
;     const float* pw = pool_w + (size_t)(g * 128 + (kb & 127)) * 128;
; #pragma unroll 2
;     for (int d = 0; d < 128; d += 4) {
;       const f32x4 ps = *(const f32x4*)(pool_s + g * 128 + d);
;       float wv[4];
;       for (int q = 0; q < 4; ++q) wv[q] = ps[q] * w_branch[(long)(g * 128 + d + q) * DM + n];
;       for (int jj = 0; jj < 4; ++jj) {
;         const f32x4 p4 = *(const f32x4*)(pw + jj * 128 + d);
;         accv[jj] += p4[0] * wv[0] + p4[1] * wv[1] + p4[2] * wv[2] + p4[3] * wv[3];
;       }
;     }
	v_add_co_u32_e32 v182, vcc, 0xffff9000, v6
	v_lshl_add_u64 v[146:147], v[8:9], 0, s[14:15]
	s_nop 0
	v_addc_co_u32_e32 v183, vcc, -1, v7, vcc
	v_add_co_u32_e32 v186, vcc, 0xffffa000, v6
	v_lshl_add_u64 v[178:179], v[12:13], 0, s[14:15]
	s_nop 0
	v_addc_co_u32_e32 v187, vcc, -1, v7, vcc
	v_add_co_u32_e32 v190, vcc, 0xffffb000, v6
	v_add_co_u32_e64 v184, s[8:9], s21, v6
	s_nop 0
	v_addc_co_u32_e32 v191, vcc, -1, v7, vcc
	v_addc_co_u32_e64 v185, s[8:9], -1, v7, s[8:9]
	global_load_dwordx4 v[142:145], v[146:147], off
	s_nop 0
	global_load_dwordx4 v[146:149], v[146:147], off offset:-16
	s_nop 0
	global_load_dwordx4 v[150:153], v[178:179], off offset:16
	global_load_dwordx4 v[154:157], v[178:179], off
	global_load_dwordx4 v[158:161], v[178:179], off offset:528
	global_load_dwordx4 v[162:165], v[178:179], off offset:512
	global_load_dwordx4 v[166:169], v[178:179], off offset:1040
	global_load_dwordx4 v[170:173], v[178:179], off offset:1024
	global_load_dwordx4 v[174:177], v[178:179], off offset:1552
	s_nop 0
	global_load_dwordx4 v[178:181], v[178:179], off offset:1536
	s_nop 0
	global_load_dword v188, v[184:185], off offset:-4096
	global_load_dword v189, v[184:185], off
	s_nop 0
	global_load_dword v184, v[6:7], off offset:-4096
	s_nop 0
	global_load_dword v182, v[182:183], off
	s_nop 0
	global_load_dword v183, v[186:187], off
	v_add_co_u32_e32 v186, vcc, 0xffffc000, v6
	s_add_i32 s19, s19, 8
	s_nop 0
	v_addc_co_u32_e32 v187, vcc, -1, v7, vcc
	global_load_dword v190, v[190:191], off
	s_nop 0
	global_load_dword v191, v[186:187], off
	global_load_dword v185, v[6:7], off
	s_add_u32 s14, s14, 32
	s_addc_u32 s15, s15, 0
	v_lshl_add_u64 v[6:7], v[6:7], 0, s[44:45]
	s_waitcnt vmcnt(48)
	v_pk_mov_b32 v[58:59], v[26:27], v[34:35] op_sel:[1,0]
	v_mov_b32_e32 v27, v35
	v_mov_b32_e32 v34, v28
	v_mov_b32_e32 v35, v36
	v_mov_b32_e32 v36, v29
	v_pk_mov_b32 v[28:29], v[22:23], v[30:31] op_sel:[1,0]
	s_waitcnt vmcnt(42)
	v_pk_mul_f32 v[14:15], v[14:15], v[60:61]
	v_mov_b32_e32 v23, v31
	v_mov_b32_e32 v30, v24
	v_mul_f32_e32 v24, v15, v39
	v_pk_mul_f32 v[22:23], v[14:15], v[22:23]
	s_waitcnt vmcnt(39)
	v_pk_mul_f32 v[18:19], v[18:19], v[54:55]
	v_mov_b32_e32 v31, v32
	v_mov_b32_e32 v32, v25
	s_waitcnt vmcnt(36)
	v_pk_mul_f32 v[16:17], v[16:17], v[56:57]
	v_mul_f32_e32 v56, v14, v46
	v_pk_fma_f32 v[24:25], v[14:15], v[38:39], v[24:25] op_sel_hi:[1,1,0]
	v_pk_fma_f32 v[38:39], v[14:15], v[46:47], v[56:57] op_sel_hi:[1,1,0]
	v_pk_fma_f32 v[14:15], v[14:15], v[28:29], v[22:23] op_sel:[1,0,0] op_sel_hi:[0,1,1]
	v_mul_f32_e32 v22, v19, v43
	v_mul_f32_e32 v28, v18, v50
	v_pk_mul_f32 v[26:27], v[18:19], v[26:27]
	v_pk_fma_f32 v[22:23], v[18:19], v[42:43], v[22:23] op_sel_hi:[1,1,0]
	v_pk_fma_f32 v[28:29], v[18:19], v[50:51], v[28:29] op_sel_hi:[1,1,0]
	v_pk_mul_f32 v[20:21], v[20:21], v[62:63]
	v_pk_fma_f32 v[18:19], v[18:19], v[58:59], v[26:27] op_sel:[1,0,0] op_sel_hi:[0,1,1]
	v_pk_mul_f32 v[48:49], v[16:17], v[48:49]
	v_pk_fma_f32 v[18:19], v[20:21], v[34:35], v[18:19] op_sel_hi:[0,1,1]
	v_pk_mul_f32 v[26:27], v[20:21], v[52:53]
	v_pk_fma_f32 v[14:15], v[16:17], v[30:31], v[14:15] op_sel_hi:[0,1,1]
	v_mul_f32_e32 v38, v16, v40
	v_mov_b32_e32 v25, v48
	v_mul_f32_e32 v28, v20, v44
	v_pk_fma_f32 v[18:19], v[20:21], v[36:37], v[18:19] op_sel:[1,0,0]
	v_mov_b32_e32 v23, v26
	v_mul_f32_e32 v60, v17, v41
	v_pk_fma_f32 v[14:15], v[16:17], v[32:33], v[14:15] op_sel:[1,0,0]
	v_pk_add_f32 v[16:17], v[24:25], v[38:39]
	v_mul_f32_e32 v24, v21, v45
	v_mov_b32_e32 v25, v27
	v_pk_add_f32 v[4:5], v[4:5], v[18:19]
	v_pk_add_f32 v[18:19], v[22:23], v[28:29]
	v_mov_b32_e32 v61, v49
	v_pk_add_f32 v[18:19], v[24:25], v[18:19]
	v_pk_add_f32 v[16:17], v[60:61], v[16:17]
	v_pk_add_f32 v[10:11], v[10:11], v[18:19]
	v_pk_add_f32 v[4:5], v[4:5], v[14:15]
	v_pk_add_f32 v[10:11], v[10:11], v[16:17]
	v_add_co_u32_e32 v54, vcc, 0xffff9000, v6
	v_lshl_add_u64 v[18:19], v[8:9], 0, s[14:15]
	s_nop 0
	v_addc_co_u32_e32 v55, vcc, -1, v7, vcc
	v_add_co_u32_e32 v58, vcc, 0xffffa000, v6
	v_lshl_add_u64 v[50:51], v[12:13], 0, s[14:15]
	s_nop 0
	v_addc_co_u32_e32 v59, vcc, -1, v7, vcc
	v_add_co_u32_e32 v62, vcc, 0xffffb000, v6
	v_add_co_u32_e64 v56, s[8:9], s21, v6
	s_nop 0
	v_addc_co_u32_e32 v63, vcc, -1, v7, vcc
	v_addc_co_u32_e64 v57, s[8:9], -1, v7, s[8:9]
	global_load_dwordx4 v[14:17], v[18:19], off
	s_nop 0
	global_load_dwordx4 v[18:21], v[18:19], off offset:-16
	s_nop 0
	global_load_dwordx4 v[22:25], v[50:51], off offset:16
	global_load_dwordx4 v[26:29], v[50:51], off
	global_load_dwordx4 v[30:33], v[50:51], off offset:528
	global_load_dwordx4 v[34:37], v[50:51], off offset:512
	global_load_dwordx4 v[38:41], v[50:51], off offset:1040
	global_load_dwordx4 v[42:45], v[50:51], off offset:1024
	global_load_dwordx4 v[46:49], v[50:51], off offset:1552
	s_nop 0
	global_load_dwordx4 v[50:53], v[50:51], off offset:1536
	s_nop 0
	global_load_dword v60, v[56:57], off offset:-4096
	global_load_dword v61, v[56:57], off
	s_nop 0
	global_load_dword v56, v[6:7], off offset:-4096
	s_nop 0
	global_load_dword v54, v[54:55], off
	s_nop 0
	global_load_dword v55, v[58:59], off
	v_add_co_u32_e32 v58, vcc, 0xffffc000, v6
	s_add_i32 s19, s19, 8
	s_nop 0
	v_addc_co_u32_e32 v59, vcc, -1, v7, vcc
	global_load_dword v62, v[62:63], off
	s_nop 0
	global_load_dword v63, v[58:59], off
	global_load_dword v57, v[6:7], off
	s_add_u32 s14, s14, 32
	s_addc_u32 s15, s15, 0
	v_lshl_add_u64 v[6:7], v[6:7], 0, s[44:45]
	s_waitcnt vmcnt(48)
	v_pk_mov_b32 v[122:123], v[90:91], v[98:99] op_sel:[1,0]
	v_mov_b32_e32 v91, v99
	v_mov_b32_e32 v98, v92
	v_mov_b32_e32 v99, v100
	v_mov_b32_e32 v100, v93
	v_pk_mov_b32 v[92:93], v[86:87], v[94:95] op_sel:[1,0]
	s_waitcnt vmcnt(42)
;     ...
;     const float* pw = pool_w + (size_t)(g * 128 + (kb & 127)) * 128;
; #pragma unroll 2
;     for (int d = 0; d < 128; d += 4) {
;       const f32x4 ps = *(const f32x4*)(pool_s + g * 128 + d);
;       float wv[4];
;       for (int q = 0; q < 4; ++q) wv[q] = ps[q] * w_branch[(long)(g * 128 + d + q) * DM + n];
;       for (int jj = 0; jj < 4; ++jj) {
;         const f32x4 p4 = *(const f32x4*)(pw + jj * 128 + d);
;         accv[jj] += p4[0] * wv[0] + p4[1] * wv[1] + p4[2] * wv[2] + p4[3] * wv[3];
;       }
;     }
	v_pk_mul_f32 v[78:79], v[78:79], v[124:125]
	v_mov_b32_e32 v87, v95
	v_mov_b32_e32 v94, v88
	v_mul_f32_e32 v88, v79, v103
	v_pk_mul_f32 v[86:87], v[78:79], v[86:87]
	s_waitcnt vmcnt(39)
	v_pk_mul_f32 v[82:83], v[82:83], v[118:119]
	v_mov_b32_e32 v95, v96
	v_mov_b32_e32 v96, v89
	s_waitcnt vmcnt(36)
	v_pk_mul_f32 v[80:81], v[80:81], v[120:121]
	v_mul_f32_e32 v120, v78, v110
	v_pk_fma_f32 v[88:89], v[78:79], v[102:103], v[88:89] op_sel_hi:[1,1,0]
	v_pk_fma_f32 v[102:103], v[78:79], v[110:111], v[120:121] op_sel_hi:[1,1,0]
	v_pk_fma_f32 v[78:79], v[78:79], v[92:93], v[86:87] op_sel:[1,0,0] op_sel_hi:[0,1,1]
	v_mul_f32_e32 v86, v83, v107
	v_mul_f32_e32 v92, v82, v114
	v_pk_mul_f32 v[90:91], v[82:83], v[90:91]
	v_pk_fma_f32 v[86:87], v[82:83], v[106:107], v[86:87] op_sel_hi:[1,1,0]
	v_pk_fma_f32 v[92:93], v[82:83], v[114:115], v[92:93] op_sel_hi:[1,1,0]
	v_pk_mul_f32 v[84:85], v[84:85], v[126:127]
	v_pk_fma_f32 v[82:83], v[82:83], v[122:123], v[90:91] op_sel:[1,0,0] op_sel_hi:[0,1,1]
	v_pk_mul_f32 v[112:113], v[80:81], v[112:113]
	v_pk_fma_f32 v[82:83], v[84:85], v[98:99], v[82:83] op_sel_hi:[0,1,1]
	v_pk_mul_f32 v[90:91], v[84:85], v[116:117]
	v_pk_fma_f32 v[78:79], v[80:81], v[94:95], v[78:79] op_sel_hi:[0,1,1]
	v_mul_f32_e32 v102, v80, v104
	v_mov_b32_e32 v89, v112
	v_mul_f32_e32 v92, v84, v108
	v_pk_fma_f32 v[82:83], v[84:85], v[100:101], v[82:83] op_sel:[1,0,0]
	v_mov_b32_e32 v87, v90
	v_mul_f32_e32 v124, v81, v105
	v_pk_fma_f32 v[78:79], v[80:81], v[96:97], v[78:79] op_sel:[1,0,0]
	v_pk_add_f32 v[80:81], v[88:89], v[102:103]
	v_mul_f32_e32 v88, v85, v109
	v_mov_b32_e32 v89, v91
	v_pk_add_f32 v[4:5], v[4:5], v[82:83]
	v_pk_add_f32 v[82:83], v[86:87], v[92:93]
	v_mov_b32_e32 v125, v113
	v_pk_add_f32 v[82:83], v[88:89], v[82:83]
	v_pk_add_f32 v[80:81], v[124:125], v[80:81]
	v_pk_add_f32 v[10:11], v[10:11], v[82:83]
	v_pk_add_f32 v[4:5], v[4:5], v[78:79]
	v_pk_add_f32 v[10:11], v[10:11], v[80:81]
	v_add_co_u32_e32 v118, vcc, 0xffff9000, v6
	v_lshl_add_u64 v[82:83], v[8:9], 0, s[14:15]
	s_nop 0
	v_addc_co_u32_e32 v119, vcc, -1, v7, vcc
	v_add_co_u32_e32 v122, vcc, 0xffffa000, v6
	v_lshl_add_u64 v[114:115], v[12:13], 0, s[14:15]
	s_nop 0
	v_addc_co_u32_e32 v123, vcc, -1, v7, vcc
	v_add_co_u32_e32 v126, vcc, 0xffffb000, v6
	v_add_co_u32_e64 v120, s[8:9], s21, v6
	s_nop 0
	v_addc_co_u32_e32 v127, vcc, -1, v7, vcc
	v_addc_co_u32_e64 v121, s[8:9], -1, v7, s[8:9]
	global_load_dwordx4 v[78:81], v[82:83], off
	s_nop 0
	global_load_dwordx4 v[82:85], v[82:83], off offset:-16
	s_nop 0
	global_load_dwordx4 v[86:89], v[114:115], off offset:16
	global_load_dwordx4 v[90:93], v[114:115], off
	global_load_dwordx4 v[94:97], v[114:115], off offset:528
	global_load_dwordx4 v[98:101], v[114:115], off offset:512
	global_load_dwordx4 v[102:105], v[114:115], off offset:1040
	global_load_dwordx4 v[106:109], v[114:115], off offset:1024
	global_load_dwordx4 v[110:113], v[114:115], off offset:1552
	s_nop 0
	global_load_dwordx4 v[114:117], v[114:115], off offset:1536
	s_nop 0
	global_load_dword v124, v[120:121], off offset:-4096
	global_load_dword v125, v[120:121], off
	s_nop 0
	global_load_dword v120, v[6:7], off offset:-4096
	s_nop 0
	global_load_dword v118, v[118:119], off
	s_nop 0
	global_load_dword v119, v[122:123], off
	v_add_co_u32_e32 v122, vcc, 0xffffc000, v6
	s_add_i32 s19, s19, 8
	s_nop 0
	v_addc_co_u32_e32 v123, vcc, -1, v7, vcc
	global_load_dword v126, v[126:127], off
	s_nop 0
	global_load_dword v127, v[122:123], off
	global_load_dword v121, v[6:7], off
	s_add_u32 s14, s14, 32
	s_addc_u32 s15, s15, 0
	v_lshl_add_u64 v[6:7], v[6:7], 0, s[44:45]
	s_waitcnt vmcnt(48)
	v_pk_mov_b32 v[186:187], v[154:155], v[162:163] op_sel:[1,0]
	v_mov_b32_e32 v155, v163
	v_mov_b32_e32 v162, v156
	v_mov_b32_e32 v163, v164
	v_mov_b32_e32 v164, v157
	v_pk_mov_b32 v[156:157], v[150:151], v[158:159] op_sel:[1,0]
	s_waitcnt vmcnt(42)
	v_pk_mul_f32 v[142:143], v[142:143], v[188:189]
	v_mov_b32_e32 v151, v159
	v_mov_b32_e32 v158, v152
	v_mul_f32_e32 v152, v143, v167
	v_pk_mul_f32 v[150:151], v[142:143], v[150:151]
	s_waitcnt vmcnt(39)
	v_pk_mul_f32 v[146:147], v[146:147], v[182:183]
	v_mov_b32_e32 v159, v160
	v_mov_b32_e32 v160, v153
	s_waitcnt vmcnt(36)
	v_pk_mul_f32 v[144:145], v[144:145], v[184:185]
	v_mul_f32_e32 v184, v142, v174
	v_pk_fma_f32 v[152:153], v[142:143], v[166:167], v[152:153] op_sel_hi:[1,1,0]
	v_pk_fma_f32 v[166:167], v[142:143], v[174:175], v[184:185] op_sel_hi:[1,1,0]
	v_pk_fma_f32 v[142:143], v[142:143], v[156:157], v[150:151] op_sel:[1,0,0] op_sel_hi:[0,1,1]
	v_mul_f32_e32 v150, v147, v171
	v_mul_f32_e32 v156, v146, v178
	v_pk_mul_f32 v[154:155], v[146:147], v[154:155]
	v_pk_fma_f32 v[150:151], v[146:147], v[170:171], v[150:151] op_sel_hi:[1,1,0]
	v_pk_fma_f32 v[156:157], v[146:147], v[178:179], v[156:157] op_sel_hi:[1,1,0]
	v_pk_mul_f32 v[148:149], v[148:149], v[190:191]
	v_pk_fma_f32 v[146:147], v[146:147], v[186:187], v[154:155] op_sel:[1,0,0] op_sel_hi:[0,1,1]
	v_pk_mul_f32 v[176:177], v[144:145], v[176:177]
	v_pk_fma_f32 v[146:147], v[148:149], v[162:163], v[146:147] op_sel_hi:[0,1,1]
	v_pk_mul_f32 v[154:155], v[148:149], v[180:181]
	v_pk_fma_f32 v[142:143], v[144:145], v[158:159], v[142:143] op_sel_hi:[0,1,1]
	v_mul_f32_e32 v166, v144, v168
	v_mov_b32_e32 v153, v176
	v_mul_f32_e32 v156, v148, v172
	v_pk_fma_f32 v[146:147], v[148:149], v[164:165], v[146:147] op_sel:[1,0,0]
	v_mov_b32_e32 v151, v154
	v_mul_f32_e32 v188, v145, v169
	v_pk_fma_f32 v[142:143], v[144:145], v[160:161], v[142:143] op_sel:[1,0,0]
	v_pk_add_f32 v[144:145], v[152:153], v[166:167]
	v_mul_f32_e32 v152, v149, v173
	v_mov_b32_e32 v153, v155
	v_pk_add_f32 v[4:5], v[4:5], v[146:147]
;     ...
;     const float* pw = pool_w + (size_t)(g * 128 + (kb & 127)) * 128;
; #pragma unroll 2
;     for (int d = 0; d < 128; d += 4) {
;       const f32x4 ps = *(const f32x4*)(pool_s + g * 128 + d);
;       float wv[4];
;       for (int q = 0; q < 4; ++q) wv[q] = ps[q] * w_branch[(long)(g * 128 + d + q) * DM + n];
;       for (int jj = 0; jj < 4; ++jj) {
;         const f32x4 p4 = *(const f32x4*)(pw + jj * 128 + d);
;         accv[jj] += p4[0] * wv[0] + p4[1] * wv[1] + p4[2] * wv[2] + p4[3] * wv[3];
;       }
;     }
	v_pk_add_f32 v[146:147], v[150:151], v[156:157]
	v_mov_b32_e32 v189, v177
	v_pk_add_f32 v[146:147], v[152:153], v[146:147]
	v_pk_add_f32 v[144:145], v[188:189], v[144:145]
	v_pk_add_f32 v[10:11], v[10:11], v[146:147]
	v_pk_add_f32 v[4:5], v[4:5], v[142:143]
	v_pk_add_f32 v[10:11], v[10:11], v[144:145]
	v_add_co_u32_e32 v182, vcc, 0xffff9000, v6
	v_lshl_add_u64 v[146:147], v[8:9], 0, s[14:15]
	s_nop 0
	v_addc_co_u32_e32 v183, vcc, -1, v7, vcc
	v_add_co_u32_e32 v186, vcc, 0xffffa000, v6
	v_lshl_add_u64 v[178:179], v[12:13], 0, s[14:15]
	s_nop 0
	v_addc_co_u32_e32 v187, vcc, -1, v7, vcc
	v_add_co_u32_e32 v190, vcc, 0xffffb000, v6
	v_add_co_u32_e64 v184, s[8:9], s21, v6
	s_nop 0
	v_addc_co_u32_e32 v191, vcc, -1, v7, vcc
	v_addc_co_u32_e64 v185, s[8:9], -1, v7, s[8:9]
	global_load_dwordx4 v[142:145], v[146:147], off
	s_nop 0
	global_load_dwordx4 v[146:149], v[146:147], off offset:-16
	s_nop 0
	global_load_dwordx4 v[150:153], v[178:179], off offset:16
	global_load_dwordx4 v[154:157], v[178:179], off
	global_load_dwordx4 v[158:161], v[178:179], off offset:528
	global_load_dwordx4 v[162:165], v[178:179], off offset:512
	global_load_dwordx4 v[166:169], v[178:179], off offset:1040
	global_load_dwordx4 v[170:173], v[178:179], off offset:1024
	global_load_dwordx4 v[174:177], v[178:179], off offset:1552
	s_nop 0
	global_load_dwordx4 v[178:181], v[178:179], off offset:1536
	s_nop 0
	global_load_dword v188, v[184:185], off offset:-4096
	global_load_dword v189, v[184:185], off
	s_nop 0
	global_load_dword v184, v[6:7], off offset:-4096
	s_nop 0
	global_load_dword v182, v[182:183], off
	s_nop 0
	global_load_dword v183, v[186:187], off
	v_add_co_u32_e32 v186, vcc, 0xffffc000, v6
	s_add_i32 s19, s19, 8
	s_nop 0
	v_addc_co_u32_e32 v187, vcc, -1, v7, vcc
	global_load_dword v190, v[190:191], off
	s_nop 0
	global_load_dword v191, v[186:187], off
	global_load_dword v185, v[6:7], off
	s_add_u32 s14, s14, 32
	s_addc_u32 s15, s15, 0
	v_lshl_add_u64 v[6:7], v[6:7], 0, s[44:45]
	s_waitcnt vmcnt(48)
	v_pk_mov_b32 v[58:59], v[26:27], v[34:35] op_sel:[1,0]
	v_mov_b32_e32 v27, v35
	v_mov_b32_e32 v34, v28
	v_mov_b32_e32 v35, v36
	v_mov_b32_e32 v36, v29
	v_pk_mov_b32 v[28:29], v[22:23], v[30:31] op_sel:[1,0]
	s_waitcnt vmcnt(42)
	v_pk_mul_f32 v[14:15], v[14:15], v[60:61]
	v_mov_b32_e32 v23, v31
	v_mov_b32_e32 v30, v24
	v_mul_f32_e32 v24, v15, v39
	v_pk_mul_f32 v[22:23], v[14:15], v[22:23]
	s_waitcnt vmcnt(39)
	v_pk_mul_f32 v[18:19], v[18:19], v[54:55]
	v_mov_b32_e32 v31, v32
	v_mov_b32_e32 v32, v25
	s_waitcnt vmcnt(36)
	v_pk_mul_f32 v[16:17], v[16:17], v[56:57]
	v_mul_f32_e32 v56, v14, v46
	v_pk_fma_f32 v[24:25], v[14:15], v[38:39], v[24:25] op_sel_hi:[1,1,0]
	v_pk_fma_f32 v[38:39], v[14:15], v[46:47], v[56:57] op_sel_hi:[1,1,0]
	v_pk_fma_f32 v[14:15], v[14:15], v[28:29], v[22:23] op_sel:[1,0,0] op_sel_hi:[0,1,1]
	v_mul_f32_e32 v22, v19, v43
	v_mul_f32_e32 v28, v18, v50
	v_pk_mul_f32 v[26:27], v[18:19], v[26:27]
	v_pk_fma_f32 v[22:23], v[18:19], v[42:43], v[22:23] op_sel_hi:[1,1,0]
	v_pk_fma_f32 v[28:29], v[18:19], v[50:51], v[28:29] op_sel_hi:[1,1,0]
	v_pk_mul_f32 v[20:21], v[20:21], v[62:63]
	v_pk_fma_f32 v[18:19], v[18:19], v[58:59], v[26:27] op_sel:[1,0,0] op_sel_hi:[0,1,1]
	v_pk_mul_f32 v[48:49], v[16:17], v[48:49]
	v_pk_fma_f32 v[18:19], v[20:21], v[34:35], v[18:19] op_sel_hi:[0,1,1]
	v_pk_mul_f32 v[26:27], v[20:21], v[52:53]
	v_pk_fma_f32 v[14:15], v[16:17], v[30:31], v[14:15] op_sel_hi:[0,1,1]
	v_mul_f32_e32 v38, v16, v40
	v_mov_b32_e32 v25, v48
	v_mul_f32_e32 v28, v20, v44
	v_pk_fma_f32 v[18:19], v[20:21], v[36:37], v[18:19] op_sel:[1,0,0]
	v_mov_b32_e32 v23, v26
	v_mul_f32_e32 v60, v17, v41
	v_pk_fma_f32 v[14:15], v[16:17], v[32:33], v[14:15] op_sel:[1,0,0]
	v_pk_add_f32 v[16:17], v[24:25], v[38:39]
	v_mul_f32_e32 v24, v21, v45
	v_mov_b32_e32 v25, v27
	v_pk_add_f32 v[4:5], v[4:5], v[18:19]
	v_pk_add_f32 v[18:19], v[22:23], v[28:29]
	v_mov_b32_e32 v61, v49
	v_pk_add_f32 v[18:19], v[24:25], v[18:19]
	v_pk_add_f32 v[16:17], v[60:61], v[16:17]
	v_pk_add_f32 v[10:11], v[10:11], v[18:19]
	v_pk_add_f32 v[4:5], v[4:5], v[14:15]
	v_pk_add_f32 v[10:11], v[10:11], v[16:17]
	v_add_co_u32_e32 v54, vcc, 0xffff9000, v6
	v_lshl_add_u64 v[18:19], v[8:9], 0, s[14:15]
	s_nop 0
	v_addc_co_u32_e32 v55, vcc, -1, v7, vcc
	v_add_co_u32_e32 v58, vcc, 0xffffa000, v6
	v_lshl_add_u64 v[50:51], v[12:13], 0, s[14:15]
	s_nop 0
	v_addc_co_u32_e32 v59, vcc, -1, v7, vcc
	v_add_co_u32_e32 v62, vcc, 0xffffb000, v6
	v_add_co_u32_e64 v56, s[8:9], s21, v6
	s_nop 0
	v_addc_co_u32_e32 v63, vcc, -1, v7, vcc
	v_addc_co_u32_e64 v57, s[8:9], -1, v7, s[8:9]
	global_load_dwordx4 v[14:17], v[18:19], off
	s_nop 0
	global_load_dwordx4 v[18:21], v[18:19], off offset:-16
	s_nop 0
	global_load_dwordx4 v[22:25], v[50:51], off offset:16
	global_load_dwordx4 v[26:29], v[50:51], off
	global_load_dwordx4 v[30:33], v[50:51], off offset:528
	global_load_dwordx4 v[34:37], v[50:51], off offset:512
	global_load_dwordx4 v[38:41], v[50:51], off offset:1040
	global_load_dwordx4 v[42:45], v[50:51], off offset:1024
	global_load_dwordx4 v[46:49], v[50:51], off offset:1552
	s_nop 0
	global_load_dwordx4 v[50:53], v[50:51], off offset:1536
	s_nop 0
	global_load_dword v60, v[56:57], off offset:-4096
	global_load_dword v61, v[56:57], off
	s_nop 0
	global_load_dword v56, v[6:7], off offset:-4096
	s_nop 0
	global_load_dword v54, v[54:55], off
	s_nop 0
	global_load_dword v55, v[58:59], off
	v_add_co_u32_e32 v58, vcc, 0xffffc000, v6
	s_add_i32 s19, s19, 8
	s_nop 0
	v_addc_co_u32_e32 v59, vcc, -1, v7, vcc
	global_load_dword v62, v[62:63], off
	s_nop 0
	global_load_dword v63, v[58:59], off
	global_load_dword v57, v[6:7], off
	s_add_u32 s14, s14, 32
	s_addc_u32 s15, s15, 0
	v_lshl_add_u64 v[6:7], v[6:7], 0, s[44:45]
	s_waitcnt vmcnt(48)
;     ...
;     const float* pw = pool_w + (size_t)(g * 128 + (kb & 127)) * 128;
; #pragma unroll 2
;     for (int d = 0; d < 128; d += 4) {
;       const f32x4 ps = *(const f32x4*)(pool_s + g * 128 + d);
;       float wv[4];
;       for (int q = 0; q < 4; ++q) wv[q] = ps[q] * w_branch[(long)(g * 128 + d + q) * DM + n];
;       for (int jj = 0; jj < 4; ++jj) {
;         const f32x4 p4 = *(const f32x4*)(pw + jj * 128 + d);
;         accv[jj] += p4[0] * wv[0] + p4[1] * wv[1] + p4[2] * wv[2] + p4[3] * wv[3];
;       }
;     }
	v_pk_mov_b32 v[122:123], v[90:91], v[98:99] op_sel:[1,0]
	v_mov_b32_e32 v91, v99
	v_mov_b32_e32 v98, v92
	v_mov_b32_e32 v99, v100
	v_mov_b32_e32 v100, v93
	v_pk_mov_b32 v[92:93], v[86:87], v[94:95] op_sel:[1,0]
	s_waitcnt vmcnt(42)
	v_pk_mul_f32 v[78:79], v[78:79], v[124:125]
	v_mov_b32_e32 v87, v95
	v_mov_b32_e32 v94, v88
	v_mul_f32_e32 v88, v79, v103
	v_pk_mul_f32 v[86:87], v[78:79], v[86:87]
	s_waitcnt vmcnt(39)
	v_pk_mul_f32 v[82:83], v[82:83], v[118:119]
	v_mov_b32_e32 v95, v96
	v_mov_b32_e32 v96, v89
	s_waitcnt vmcnt(36)
	v_pk_mul_f32 v[80:81], v[80:81], v[120:121]
	v_mul_f32_e32 v120, v78, v110
	v_pk_fma_f32 v[88:89], v[78:79], v[102:103], v[88:89] op_sel_hi:[1,1,0]
	v_pk_fma_f32 v[102:103], v[78:79], v[110:111], v[120:121] op_sel_hi:[1,1,0]
	v_pk_fma_f32 v[78:79], v[78:79], v[92:93], v[86:87] op_sel:[1,0,0] op_sel_hi:[0,1,1]
	v_mul_f32_e32 v86, v83, v107
	v_mul_f32_e32 v92, v82, v114
	v_pk_mul_f32 v[90:91], v[82:83], v[90:91]
	v_pk_fma_f32 v[86:87], v[82:83], v[106:107], v[86:87] op_sel_hi:[1,1,0]
	v_pk_fma_f32 v[92:93], v[82:83], v[114:115], v[92:93] op_sel_hi:[1,1,0]
	v_pk_mul_f32 v[84:85], v[84:85], v[126:127]
	v_pk_fma_f32 v[82:83], v[82:83], v[122:123], v[90:91] op_sel:[1,0,0] op_sel_hi:[0,1,1]
	v_pk_mul_f32 v[112:113], v[80:81], v[112:113]
	v_pk_fma_f32 v[82:83], v[84:85], v[98:99], v[82:83] op_sel_hi:[0,1,1]
	v_pk_mul_f32 v[90:91], v[84:85], v[116:117]
	v_pk_fma_f32 v[78:79], v[80:81], v[94:95], v[78:79] op_sel_hi:[0,1,1]
	v_mul_f32_e32 v102, v80, v104
	v_mov_b32_e32 v89, v112
	v_mul_f32_e32 v92, v84, v108
	v_pk_fma_f32 v[82:83], v[84:85], v[100:101], v[82:83] op_sel:[1,0,0]
	v_mov_b32_e32 v87, v90
	v_mul_f32_e32 v124, v81, v105
	v_pk_fma_f32 v[78:79], v[80:81], v[96:97], v[78:79] op_sel:[1,0,0]
	v_pk_add_f32 v[80:81], v[88:89], v[102:103]
	v_mul_f32_e32 v88, v85, v109
	v_mov_b32_e32 v89, v91
	v_pk_add_f32 v[4:5], v[4:5], v[82:83]
	v_pk_add_f32 v[82:83], v[86:87], v[92:93]
	v_mov_b32_e32 v125, v113
	v_pk_add_f32 v[82:83], v[88:89], v[82:83]
	v_pk_add_f32 v[80:81], v[124:125], v[80:81]
	v_pk_add_f32 v[10:11], v[10:11], v[82:83]
	v_pk_add_f32 v[4:5], v[4:5], v[78:79]
	v_pk_add_f32 v[10:11], v[10:11], v[80:81]
	s_waitcnt vmcnt(30)
	v_pk_mov_b32 v[186:187], v[154:155], v[162:163] op_sel:[1,0]
	v_mov_b32_e32 v155, v163
	v_mov_b32_e32 v162, v156
	v_mov_b32_e32 v163, v164
	v_mov_b32_e32 v164, v157
	v_pk_mov_b32 v[156:157], v[150:151], v[158:159] op_sel:[1,0]
	s_waitcnt vmcnt(24)
	v_pk_mul_f32 v[142:143], v[142:143], v[188:189]
	v_mov_b32_e32 v151, v159
	v_mov_b32_e32 v158, v152
	v_mul_f32_e32 v152, v143, v167
	v_pk_mul_f32 v[150:151], v[142:143], v[150:151]
	s_waitcnt vmcnt(21)
	v_pk_mul_f32 v[146:147], v[146:147], v[182:183]
	v_mov_b32_e32 v159, v160
	v_mov_b32_e32 v160, v153
	s_waitcnt vmcnt(18)
; DI unsigned pack2(float a, float b) { f2_t v = {a, b}; bf2_t r = __builtin_convertvector(v, bf2_t); return __builtin_bit_cast(unsigned, r); }
; DI int get_tid(int wv) { int l; asm volatile("v_mbcnt_lo_u32_b32 %0, -1, 0\n\tv_mbcnt_hi_u32_b32 %0, -1, %0" : "=v"(l)); return wv * 64 + l; }
;     ...
;   for (int it = GRD - 1 - BID; it < (((mask >> 12) & 1) ? 16 * 16 : 0); it += GRD) {
;     const int k0 = (it >> 4) * 32, n0 = (it & 15) * 64;
;     const int tid = get_tid(WV);
;     const int n = n0 + (tid & 63), kb = k0 + (tid >> 6) * 4, g = kb >> 7;
;     float accv[4] = {0, 0, 0, 0};
;     const float* pw = pool_w + (size_t)(g * 128 + (kb & 127)) * 128;
; #pragma unroll 2
;     for (int d = 0; d < 128; d += 4) {
;       const f32x4 ps = *(const f32x4*)(pool_s + g * 128 + d);
;       float wv[4];
;       for (int q = 0; q < 4; ++q) wv[q] = ps[q] * w_branch[(long)(g * 128 + d + q) * DM + n];
;       for (int jj = 0; jj < 4; ++jj) {
;         const f32x4 p4 = *(const f32x4*)(pw + jj * 128 + d);
;         accv[jj] += p4[0] * wv[0] + p4[1] * wv[1] + p4[2] * wv[2] + p4[3] * wv[3];
;       }
;     }
;     uint2 o; o.x = pack2(accv[0], accv[1]); o.y = pack2(accv[2], accv[3]);
;     *(uint2*)(WB + (long)n * 512 + kb) = o;
	v_pk_mul_f32 v[144:145], v[144:145], v[184:185]
	v_mul_f32_e32 v184, v142, v174
	v_pk_fma_f32 v[152:153], v[142:143], v[166:167], v[152:153] op_sel_hi:[1,1,0]
	v_pk_fma_f32 v[166:167], v[142:143], v[174:175], v[184:185] op_sel_hi:[1,1,0]
	v_pk_fma_f32 v[142:143], v[142:143], v[156:157], v[150:151] op_sel:[1,0,0] op_sel_hi:[0,1,1]
	v_mul_f32_e32 v150, v147, v171
	v_mul_f32_e32 v156, v146, v178
	v_pk_mul_f32 v[154:155], v[146:147], v[154:155]
	v_pk_fma_f32 v[150:151], v[146:147], v[170:171], v[150:151] op_sel_hi:[1,1,0]
	v_pk_fma_f32 v[156:157], v[146:147], v[178:179], v[156:157] op_sel_hi:[1,1,0]
	v_pk_mul_f32 v[148:149], v[148:149], v[190:191]
	v_pk_fma_f32 v[146:147], v[146:147], v[186:187], v[154:155] op_sel:[1,0,0] op_sel_hi:[0,1,1]
	v_pk_mul_f32 v[176:177], v[144:145], v[176:177]
	v_pk_fma_f32 v[146:147], v[148:149], v[162:163], v[146:147] op_sel_hi:[0,1,1]
	v_pk_mul_f32 v[154:155], v[148:149], v[180:181]
	v_pk_fma_f32 v[142:143], v[144:145], v[158:159], v[142:143] op_sel_hi:[0,1,1]
	v_mul_f32_e32 v166, v144, v168
	v_mov_b32_e32 v153, v176
	v_mul_f32_e32 v156, v148, v172
	v_pk_fma_f32 v[146:147], v[148:149], v[164:165], v[146:147] op_sel:[1,0,0]
	v_mov_b32_e32 v151, v154
	v_mul_f32_e32 v188, v145, v169
	v_pk_fma_f32 v[142:143], v[144:145], v[160:161], v[142:143] op_sel:[1,0,0]
	v_pk_add_f32 v[144:145], v[152:153], v[166:167]
	v_mul_f32_e32 v152, v149, v173
	v_mov_b32_e32 v153, v155
	v_pk_add_f32 v[4:5], v[4:5], v[146:147]
	v_pk_add_f32 v[146:147], v[150:151], v[156:157]
	v_mov_b32_e32 v189, v177
	v_pk_add_f32 v[146:147], v[152:153], v[146:147]
	v_pk_add_f32 v[144:145], v[188:189], v[144:145]
	v_pk_add_f32 v[10:11], v[10:11], v[146:147]
	v_pk_add_f32 v[4:5], v[4:5], v[142:143]
	v_pk_add_f32 v[10:11], v[10:11], v[144:145]
	s_waitcnt vmcnt(12)
	v_pk_mov_b32 v[58:59], v[26:27], v[34:35] op_sel:[1,0]
	v_mov_b32_e32 v27, v35
	v_mov_b32_e32 v34, v28
	v_mov_b32_e32 v35, v36
	v_mov_b32_e32 v36, v29
	v_pk_mov_b32 v[28:29], v[22:23], v[30:31] op_sel:[1,0]
	s_waitcnt vmcnt(6)
	v_pk_mul_f32 v[14:15], v[14:15], v[60:61]
	v_mov_b32_e32 v23, v31
	v_mov_b32_e32 v30, v24
	v_mul_f32_e32 v24, v15, v39
	v_pk_mul_f32 v[22:23], v[14:15], v[22:23]
	s_waitcnt vmcnt(3)
	v_pk_mul_f32 v[18:19], v[18:19], v[54:55]
	v_mov_b32_e32 v31, v32
	v_mov_b32_e32 v32, v25
	s_waitcnt vmcnt(0)
	v_pk_mul_f32 v[16:17], v[16:17], v[56:57]
	v_mul_f32_e32 v56, v14, v46
	v_pk_fma_f32 v[24:25], v[14:15], v[38:39], v[24:25] op_sel_hi:[1,1,0]
	v_pk_fma_f32 v[38:39], v[14:15], v[46:47], v[56:57] op_sel_hi:[1,1,0]
	v_pk_fma_f32 v[14:15], v[14:15], v[28:29], v[22:23] op_sel:[1,0,0] op_sel_hi:[0,1,1]
	v_mul_f32_e32 v22, v19, v43
	v_mul_f32_e32 v28, v18, v50
	v_pk_mul_f32 v[26:27], v[18:19], v[26:27]
	v_pk_fma_f32 v[22:23], v[18:19], v[42:43], v[22:23] op_sel_hi:[1,1,0]
	v_pk_fma_f32 v[28:29], v[18:19], v[50:51], v[28:29] op_sel_hi:[1,1,0]
	v_pk_mul_f32 v[20:21], v[20:21], v[62:63]
	v_pk_fma_f32 v[18:19], v[18:19], v[58:59], v[26:27] op_sel:[1,0,0] op_sel_hi:[0,1,1]
	v_pk_mul_f32 v[48:49], v[16:17], v[48:49]
	v_pk_fma_f32 v[18:19], v[20:21], v[34:35], v[18:19] op_sel_hi:[0,1,1]
	v_pk_mul_f32 v[26:27], v[20:21], v[52:53]
	v_pk_fma_f32 v[14:15], v[16:17], v[30:31], v[14:15] op_sel_hi:[0,1,1]
	v_mul_f32_e32 v38, v16, v40
	v_mov_b32_e32 v25, v48
	v_mul_f32_e32 v28, v20, v44
	v_pk_fma_f32 v[18:19], v[20:21], v[36:37], v[18:19] op_sel:[1,0,0]
	v_mov_b32_e32 v23, v26
	v_mul_f32_e32 v60, v17, v41
	v_pk_fma_f32 v[14:15], v[16:17], v[32:33], v[14:15] op_sel:[1,0,0]
	v_pk_add_f32 v[16:17], v[24:25], v[38:39]
	v_mul_f32_e32 v24, v21, v45
	v_mov_b32_e32 v25, v27
	v_pk_add_f32 v[4:5], v[4:5], v[18:19]
	v_pk_add_f32 v[18:19], v[22:23], v[28:29]
	v_mov_b32_e32 v61, v49
	v_pk_add_f32 v[18:19], v[24:25], v[18:19]
	v_pk_add_f32 v[16:17], v[60:61], v[16:17]
	v_pk_add_f32 v[10:11], v[10:11], v[18:19]
	v_pk_add_f32 v[4:5], v[4:5], v[14:15]
	v_pk_add_f32 v[10:11], v[10:11], v[16:17]
	s_lshl_b32 s8, s0, 1
	s_lshl_b32 s9, s0, 6
	s_andn2_b32 s8, s8, 31
	s_and_b32 s9, s9, 0x3c0
	v_or_b32_e32 v0, s9, v0
	v_add_u32_e32 v2, s8, v2
	v_readlane_b32 s8, v255, 35
	v_lshlrev_b32_e32 v0, 10, v0
	v_readlane_b32 s9, v255, 36
	v_ashrrev_i32_e32 v3, 31, v2
	s_add_i32 s0, s0, s20
	v_lshl_add_u64 v[6:7], s[8:9], 0, v[0:1]
	s_add_i32 s1, s1, s16
	s_add_i32 s17, s17, s18
	v_cvt_pk_bf16_f32 v4, v4, v5
	v_cvt_pk_bf16_f32 v5, v10, v11
	v_lshl_add_u64 v[2:3], v[2:3], 1, v[6:7]
	s_cmpk_gt_i32 s0, 0xff
	global_store_dwordx2 v[2:3], v[4:5], off
	s_cbranch_scc0 .LBB0_409
